# P9 body rewritten by hand: one big work grab per workgroup (no per-chunk atomics/barriers), 32-bit row offsets, 32 gathers in flight, DPP transposing reduction; P5 epilogue loads batched
# speedup vs baseline: 1.0311x; 1.0167x over previous
; DI unsigned pk2(float a, float b) { f2_t v = {a, b}; bf2_t r = __builtin_convertvector(v, bf2_t); return __builtin_bit_cast(unsigned, r); }
; DI void phase5(const Params& p, char* smem) {
;     ...
;     gemm_tile<true>(MG, D_, W, D_, D_, tm * 128, tn * 128, smem, [&](f32x16 (&acc)[2][2], int mb, int nb, int r, int hi) __attribute__((always_inline)) {
; #pragma unroll
;       for (int mi = 0; mi < 2; ++mi) {
;         const int row = mb + mi * 32 + r, b = row >> 11;
;         const float* gt = mod + b * 12288 + 2 * 2048;
; #pragma unroll
;         for (int ni = 0; ni < 2; ++ni)
; #pragma unroll
;           for (int g = 0; g < 4; ++g) {
;             const int col = nb + ni * 32 + hi * 4 + 8 * g;
;             const float4 xv = *(const float4*)(X + (size_t)row * D_ + col), gv = *(const float4*)(gt + col);
;             float4 o;
;             o.x = xv.x + gv.x * acc[mi][ni][4 * g]; o.y = xv.y + gv.y * acc[mi][ni][4 * g + 1]; o.z = xv.z + gv.z * acc[mi][ni][4 * g + 2]; o.w = xv.w + gv.w * acc[mi][ni][4 * g + 3];
;             *(uint2*)(X1 + (size_t)row * D_ + col) = make_uint2(pk2(o.x, o.y), pk2(o.z, o.w));
;           }
;       }
;     });
.LBB0_745:
	v_add_u32_e32 v190, s18, v146
	v_ashrrev_i32_e32 v192, 11, v190
	v_mul_i32_i24_e32 v192, 0x3000, v192
	v_ashrrev_i32_e32 v193, 31, v192
	v_or_b32_e32 v194, s19, v149
	v_lshl_add_u64 v[192:193], v[192:193], 2, s[82:83]
	v_ashrrev_i32_e32 v191, 31, v190
	v_lshl_add_u64 v[196:197], v[192:193], 0, s[6:7]
	v_lshlrev_b64 v[192:193], 13, v[190:191]
	v_ashrrev_i32_e32 v195, 31, v194
	v_lshl_add_u64 v[192:193], s[56:57], 0, v[192:193]
	v_lshlrev_b64 v[198:199], 2, v[194:195]
	v_lshl_add_u64 v[200:201], v[192:193], 0, v[198:199]
	v_lshl_add_u64 v[202:203], v[196:197], 0, v[198:199]
	global_load_dwordx4 v[150:153], v[202:203], off
	global_load_dwordx4 v[154:157], v[202:203], off offset:32
	global_load_dwordx4 v[158:161], v[202:203], off offset:64
	global_load_dwordx4 v[162:165], v[202:203], off offset:96
	global_load_dwordx4 v[166:169], v[202:203], off offset:128
	global_load_dwordx4 v[170:173], v[202:203], off offset:160
	global_load_dwordx4 v[174:177], v[202:203], off offset:192
	global_load_dwordx4 v[178:181], v[202:203], off offset:224
	global_load_dwordx4 v[66:69], v[200:201], off
	global_load_dwordx4 v[70:73], v[200:201], off offset:32
	global_load_dwordx4 v[74:77], v[200:201], off offset:64
	global_load_dwordx4 v[78:81], v[200:201], off offset:96
	global_load_dwordx4 v[82:85], v[200:201], off offset:128
	global_load_dwordx4 v[86:89], v[200:201], off offset:160
	global_load_dwordx4 v[90:93], v[200:201], off offset:192
	global_load_dwordx4 v[94:97], v[200:201], off offset:224
	v_or_b32_e32 v212, 32, v190
	v_ashrrev_i32_e32 v213, 31, v212
	v_lshlrev_b64 v[208:209], 13, v[212:213]
	v_lshl_add_u64 v[208:209], s[56:57], 0, v[208:209]
	v_lshl_add_u64 v[208:209], v[208:209], 0, v[198:199]
	global_load_dwordx4 v[98:101], v[208:209], off
	global_load_dwordx4 v[102:105], v[208:209], off offset:32
	global_load_dwordx4 v[106:109], v[208:209], off offset:64
	global_load_dwordx4 v[110:113], v[208:209], off offset:96
	global_load_dwordx4 v[114:117], v[208:209], off offset:128
	global_load_dwordx4 v[118:121], v[208:209], off offset:160
	global_load_dwordx4 v[122:125], v[208:209], off offset:192
	global_load_dwordx4 v[126:129], v[208:209], off offset:224
	v_lshlrev_b64 v[204:205], 12, v[190:191]
	v_lshlrev_b64 v[206:207], 1, v[194:195]
	v_lshl_add_u64 v[204:205], s[2:3], 0, v[204:205]
	v_lshl_add_u64 v[204:205], v[204:205], 0, v[206:207]
	v_lshlrev_b64 v[210:211], 12, v[212:213]
	v_lshl_add_u64 v[210:211], s[2:3], 0, v[210:211]
	v_lshl_add_u64 v[210:211], v[210:211], 0, v[206:207]
	s_add_i32 s17, s17, s13
	s_cmpk_lt_i32 s17, 0x400
	s_waitcnt vmcnt(15)
	v_pk_fma_f32 v[50:51], v[50:51], v[150:151], v[66:67]
	v_pk_fma_f32 v[52:53], v[52:53], v[152:153], v[68:69]
	v_cvt_pk_bf16_f32 v50, v50, v51
	v_cvt_pk_bf16_f32 v51, v52, v53
	global_store_dwordx2 v[204:205], v[50:51], off
	s_waitcnt vmcnt(15)
	v_pk_fma_f32 v[54:55], v[54:55], v[154:155], v[70:71]
	v_pk_fma_f32 v[56:57], v[56:57], v[156:157], v[72:73]
	v_cvt_pk_bf16_f32 v54, v54, v55
	v_cvt_pk_bf16_f32 v55, v56, v57
	global_store_dwordx2 v[204:205], v[54:55], off offset:16
	s_waitcnt vmcnt(15)
	v_pk_fma_f32 v[58:59], v[58:59], v[158:159], v[74:75]
	v_pk_fma_f32 v[60:61], v[60:61], v[160:161], v[76:77]
	v_cvt_pk_bf16_f32 v58, v58, v59
	v_cvt_pk_bf16_f32 v59, v60, v61
	global_store_dwordx2 v[204:205], v[58:59], off offset:32
	s_waitcnt vmcnt(15)
	v_pk_fma_f32 v[62:63], v[62:63], v[162:163], v[78:79]
	v_pk_fma_f32 v[64:65], v[64:65], v[164:165], v[80:81]
	v_cvt_pk_bf16_f32 v62, v62, v63
	v_cvt_pk_bf16_f32 v63, v64, v65
	global_store_dwordx2 v[204:205], v[62:63], off offset:48
	s_waitcnt vmcnt(15)
	v_pk_fma_f32 v[34:35], v[34:35], v[166:167], v[82:83]
	v_pk_fma_f32 v[36:37], v[36:37], v[168:169], v[84:85]
	v_cvt_pk_bf16_f32 v34, v34, v35
	v_cvt_pk_bf16_f32 v35, v36, v37
	global_store_dwordx2 v[204:205], v[34:35], off offset:64
	s_waitcnt vmcnt(15)
	v_pk_fma_f32 v[38:39], v[38:39], v[170:171], v[86:87]
	v_pk_fma_f32 v[40:41], v[40:41], v[172:173], v[88:89]
	v_cvt_pk_bf16_f32 v38, v38, v39
	v_cvt_pk_bf16_f32 v39, v40, v41
	global_store_dwordx2 v[204:205], v[38:39], off offset:80
	s_waitcnt vmcnt(15)
	v_pk_fma_f32 v[42:43], v[42:43], v[174:175], v[90:91]
	v_pk_fma_f32 v[44:45], v[44:45], v[176:177], v[92:93]
	v_cvt_pk_bf16_f32 v42, v42, v43
	v_cvt_pk_bf16_f32 v43, v44, v45
	global_store_dwordx2 v[204:205], v[42:43], off offset:96
	s_waitcnt vmcnt(15)
	v_pk_fma_f32 v[46:47], v[46:47], v[178:179], v[94:95]
	v_pk_fma_f32 v[48:49], v[48:49], v[180:181], v[96:97]
	v_cvt_pk_bf16_f32 v46, v46, v47
	v_cvt_pk_bf16_f32 v47, v48, v49
	global_store_dwordx2 v[204:205], v[46:47], off offset:112
	s_waitcnt vmcnt(15)
	v_pk_fma_f32 v[18:19], v[18:19], v[150:151], v[98:99]
	v_pk_fma_f32 v[20:21], v[20:21], v[152:153], v[100:101]
	v_cvt_pk_bf16_f32 v18, v18, v19
	v_cvt_pk_bf16_f32 v19, v20, v21
	global_store_dwordx2 v[210:211], v[18:19], off
	s_waitcnt vmcnt(15)
	v_pk_fma_f32 v[22:23], v[22:23], v[154:155], v[102:103]
	v_pk_fma_f32 v[24:25], v[24:25], v[156:157], v[104:105]
	v_cvt_pk_bf16_f32 v22, v22, v23
	v_cvt_pk_bf16_f32 v23, v24, v25
	global_store_dwordx2 v[210:211], v[22:23], off offset:16
	s_waitcnt vmcnt(15)
	v_pk_fma_f32 v[26:27], v[26:27], v[158:159], v[106:107]
	v_pk_fma_f32 v[28:29], v[28:29], v[160:161], v[108:109]
	v_cvt_pk_bf16_f32 v26, v26, v27
	v_cvt_pk_bf16_f32 v27, v28, v29
	global_store_dwordx2 v[210:211], v[26:27], off offset:32
	s_waitcnt vmcnt(15)
	v_pk_fma_f32 v[30:31], v[30:31], v[162:163], v[110:111]
	v_pk_fma_f32 v[32:33], v[32:33], v[164:165], v[112:113]
	v_cvt_pk_bf16_f32 v30, v30, v31
	v_cvt_pk_bf16_f32 v31, v32, v33
	global_store_dwordx2 v[210:211], v[30:31], off offset:48
	s_waitcnt vmcnt(15)
	v_pk_fma_f32 v[2:3], v[2:3], v[166:167], v[114:115]
	v_pk_fma_f32 v[4:5], v[4:5], v[168:169], v[116:117]
	v_cvt_pk_bf16_f32 v2, v2, v3
	v_cvt_pk_bf16_f32 v3, v4, v5
	global_store_dwordx2 v[210:211], v[2:3], off offset:64
	s_waitcnt vmcnt(15)
	v_pk_fma_f32 v[6:7], v[6:7], v[170:171], v[118:119]
	v_pk_fma_f32 v[8:9], v[8:9], v[172:173], v[120:121]
	v_cvt_pk_bf16_f32 v6, v6, v7
	v_cvt_pk_bf16_f32 v7, v8, v9
	global_store_dwordx2 v[210:211], v[6:7], off offset:80
	s_waitcnt vmcnt(15)
	v_pk_fma_f32 v[10:11], v[10:11], v[174:175], v[122:123]
	v_pk_fma_f32 v[12:13], v[12:13], v[176:177], v[124:125]
	v_cvt_pk_bf16_f32 v10, v10, v11
	v_cvt_pk_bf16_f32 v11, v12, v13
	global_store_dwordx2 v[210:211], v[10:11], off offset:96
	s_waitcnt vmcnt(15)
	v_pk_fma_f32 v[14:15], v[14:15], v[178:179], v[126:127]
	v_pk_fma_f32 v[16:17], v[16:17], v[180:181], v[128:129]
	v_cvt_pk_bf16_f32 v14, v14, v15
	v_cvt_pk_bf16_f32 v15, v16, v17
	global_store_dwordx2 v[210:211], v[14:15], off offset:112
	s_cbranch_scc0 .LBB0_754

; DI unsigned xb_xcc_id() { return (unsigned)__builtin_amdgcn_s_getreg((3 << 11) | 20) & 0xFu; }
; DI void wave_lds_sync() { asm volatile("s_waitcnt lgkmcnt(0)" ::: "memory"); __builtin_amdgcn_wave_barrier(); }
; template <class F>
; DI void xcd_queue(unsigned* ctrs, int nchunks, char* smem, F&& f) {
;   const int x0 = (int)(xb_xcc_id() & 7u);
; #pragma unroll 1
;   for (int k = 0; k < 8; ++k) {
;     const int s = (x0 + k) & 7;
;     for (;;) { const int c = grab(ctrs + 64 * s, smem); if (c >= nchunks) break; f(s, c); }
;   }
; }
; DI void phase9(const Params& p, char* smem, int rep) {
;     ...
;   const int lane = threadIdx.x & 63, w = threadIdx.x >> 6, g = lane >> 4, l15 = lane & 15;
;   const int b3 = (lane >> 3) & 1, b2 = (lane >> 2) & 1, b1 = (lane >> 1) & 1, b0 = lane & 1;
;   int* lw = (int*)(smem + 16) + w * 256;
;   xcd_queue((unsigned*)(p.ws + WS_BAR) + CTR_UQ + rep * 8, 512, smem, [&](int s, int c) __attribute__((always_inline)) {
; #pragma unroll 1
;     for (int t = 0; t < 4; ++t) {
;       const int tok = __builtin_amdgcn_readfirstlane(c * 16 + w * 4 + t);
;       const int i0 = IDS[(size_t)tok * 128 + lane], i1 = IDS[(size_t)tok * 128 + 64 + lane];
;       const u32x4 hq = *(const u32x4*)(H2Q + (size_t)tok * D_ + s * 256 + l15 * 16);
;       wave_lds_sync();
;       lw[(lane & 3) * 32 + (lane >> 2)] = i0;
;       lw[(lane & 3) * 32 + 16 + (lane >> 2)] = i1;
;       wave_lds_sync();
;       const unsigned char* ub = U8 + s * 256 + l15 * 16;
; #pragma unroll
;       for (int batch = 0; batch < 2; ++batch) {
;         int ida[16];
; #pragma unroll
;         for (int q = 0; q < 4; ++q) { const int4 v = *(const int4*)(lw + g * 32 + batch * 16 + q * 4); ida[q * 4] = v.x; ida[q * 4 + 1] = v.y; ida[q * 4 + 2] = v.z; ida[q * 4 + 3] = v.w; }
;         u32x4 rows[16];
; #pragma unroll
;         for (int k = 0; k < 16; ++k) rows[k] = *(const u32x4*)(ub + (size_t)ida[k] * 2048);
.LBB0_1117:
	s_waitcnt lgkmcnt(0)
	v_and_b32_e32 v1, 63, v0
	v_and_b32_e32 v2, 15, v0
	v_bfe_u32 v3, v0, 4, 2
	v_lshl_add_u32 v4, v2, 2, v3
	v_lshlrev_b32_e32 v4, 2, v4
	v_lshlrev_b32_e32 v2, 4, v2
	v_lshrrev_b32_e32 v6, 6, v0
	v_lshlrev_b32_e32 v6, 10, v6
	v_lshlrev_b32_e32 v5, 7, v0
	v_and_b32_e32 v5, 0x180, v5
	v_and_b32_e32 v7, 60, v0
	v_add3_u32 v5, v6, v5, v7
	v_lshl_add_u32 v6, v3, 7, v6
	v_lshlrev_b32_e32 v3, 2, v1
	v_and_b32_e32 v7, 2, v0
	v_cmp_eq_u32_e64 s[2:3], 0, v7
	v_and_b32_e32 v7, 1, v0
	v_cmp_eq_u32_e64 s[4:5], 0, v7
	v_and_b32_e32 v216, 7, v0
	v_lshlrev_b32_e32 v216, 8, v216
	v_mov_b32_e32 v7, 0
	s_add_u32 s6, s82, 0x16638000
	s_addc_u32 s7, s83, 0
	s_add_u32 s8, s82, 0x17318000
	s_addc_u32 s9, s83, 0
	s_add_u32 s10, s82, 0x2538000
	s_addc_u32 s11, s83, 0
	s_add_u32 s14, s82, 0x10638000
	s_addc_u32 s15, s83, 0
	s_add_u32 s16, s82, 0x4000
	s_addc_u32 s17, s83, 0
	s_getreg_b32 s13, hwreg(HW_REG_XCC_ID, 0, 4)
	s_and_b32 s13, s13, 7
	s_mov_b32 s18, 0
	s_mov_b32 s50, 8
	s_mov_b32 s52, 0
	s_lshl_b32 s35, s13, 8
	s_add_u32 s26, s16, s35
	s_addc_u32 s27, s17, 0
	v_lshrrev_b32_e32 v9, 6, v0
	v_mov_b32_e32 v215, 8
	v_readfirstlane_b32 s53, v9
	s_cmp_eq_u32 s53, 0
	s_cbranch_scc0 .Lp9_wg_wait
	v_mov_b32_e32 v8, 128
	s_mov_b64 s[28:29], exec
	s_mov_b64 exec, 1
	global_atomic_add v9, v7, v8, s[26:27] sc0
	s_waitcnt vmcnt(0)
	ds_write_b32 v215, v9
	s_mov_b64 exec, s[28:29]
	s_waitcnt lgkmcnt(0)
.Lp9_wg_wait:
	s_barrier
	ds_read_b32 v9, v215
	s_waitcnt lgkmcnt(0)
	v_readfirstlane_b32 s34, v9
	s_nop 1
	s_mul_i32 s35, s53, 32
	s_add_i32 s34, s34, s35
	s_mov_b32 s49, 8
	s_mov_b32 s19, s13
	s_lshl_b32 s35, s19, 8
	s_add_u32 s20, s10, s35
	s_addc_u32 s21, s11, 0
	s_add_u32 s22, s8, s35
	s_addc_u32 s23, s9, 0
	s_add_u32 s26, s16, s35
	s_addc_u32 s27, s17, 0
	s_lshl_b32 s24, s19, 22
	s_cmp_ge_u32 s34, 8192
	s_cbranch_scc1 .Lp9_peek
	s_branch .Lp9_fill
.Lp9_slice:
	s_add_i32 s19, s13, s18
	s_and_b32 s19, s19, 7
	s_nop 3
	v_readlane_b32 s47, v215, s19
	s_cmp_ge_u32 s47, 8192
	s_cbranch_scc1 .Lp9_slice_next
	s_lshl_b32 s35, s19, 8
	s_add_u32 s20, s10, s35
	s_addc_u32 s21, s11, 0
	s_add_u32 s22, s8, s35
	s_addc_u32 s23, s9, 0
	s_add_u32 s26, s16, s35
	s_addc_u32 s27, s17, 0
	s_lshl_b32 s24, s19, 22
.Lp9_grab:
	v_mov_b32_e32 v8, s50
	s_mov_b64 s[28:29], exec
	s_mov_b64 exec, 1
	global_atomic_add v9, v7, v8, s[26:27] sc0
	s_mov_b64 exec, s[28:29]
	s_waitcnt vmcnt(0)
	v_readfirstlane_b32 s34, v9
	s_nop 1
	s_cmp_ge_u32 s34, 8192
	s_cbranch_scc1 .Lp9_slice_next
	s_lshr_b32 s49, s50, 2
.Lp9_fill:
	s_lshl_b32 s47, s34, 9
	s_add_u32 s42, s6, s47
	s_addc_u32 s43, s7, 0
	s_lshl_b32 s47, s34, 11
	s_add_u32 s44, s22, s47
	s_addc_u32 s45, s23, 0
	global_load_dword v10, v3, s[42:43]
	global_load_dword v11, v3, s[42:43] offset:256
	global_load_dwordx4 v[12:15], v2, s[44:45]
	s_waitcnt vmcnt(0)
	ds_write2_b32 v5, v10, v11 offset0:4 offset1:20
	s_waitcnt lgkmcnt(0)
	ds_read_b128 v[20:23], v6 offset:16
	ds_read_b128 v[24:27], v6 offset:32
	ds_read_b128 v[28:31], v6 offset:48
	ds_read_b128 v[32:35], v6 offset:64
	ds_read_b128 v[36:39], v6 offset:80
	ds_read_b128 v[40:43], v6 offset:96
	ds_read_b128 v[44:47], v6 offset:112
	ds_read_b128 v[48:51], v6 offset:128
	s_mov_b32 s48, 0
.Lp9_body:
	s_add_i32 s36, s34, 0
	s_lshl_b32 s46, s36, 9
	s_add_i32 s46, s46, s24
	s_add_i32 s37, s34, 1
	s_lshl_b32 s47, s37, 9
	s_add_u32 s42, s6, s47
	s_addc_u32 s43, s7, 0
	s_lshl_b32 s47, s37, 11
	s_add_u32 s44, s22, s47
	s_addc_u32 s45, s23, 0
	global_load_dword v10, v3, s[42:43]
	global_load_dword v11, v3, s[42:43] offset:256
	global_load_dwordx4 v[16:19], v2, s[44:45]
	s_waitcnt lgkmcnt(0)
	v_lshl_add_u32 v20, v20, 11, v2
	v_lshl_add_u32 v21, v21, 11, v2
	v_lshl_add_u32 v22, v22, 11, v2
	v_lshl_add_u32 v23, v23, 11, v2
	v_lshl_add_u32 v24, v24, 11, v2
	v_lshl_add_u32 v25, v25, 11, v2
	v_lshl_add_u32 v26, v26, 11, v2
	v_lshl_add_u32 v27, v27, 11, v2
	v_lshl_add_u32 v28, v28, 11, v2
	v_lshl_add_u32 v29, v29, 11, v2
	v_lshl_add_u32 v30, v30, 11, v2
	v_lshl_add_u32 v31, v31, 11, v2
	v_lshl_add_u32 v32, v32, 11, v2
	v_lshl_add_u32 v33, v33, 11, v2
	v_lshl_add_u32 v34, v34, 11, v2
	v_lshl_add_u32 v35, v35, 11, v2
	v_lshl_add_u32 v36, v36, 11, v2
	v_lshl_add_u32 v37, v37, 11, v2
	v_lshl_add_u32 v38, v38, 11, v2
	v_lshl_add_u32 v39, v39, 11, v2
	v_lshl_add_u32 v40, v40, 11, v2
	v_lshl_add_u32 v41, v41, 11, v2
	v_lshl_add_u32 v42, v42, 11, v2
	v_lshl_add_u32 v43, v43, 11, v2
	v_lshl_add_u32 v44, v44, 11, v2
	v_lshl_add_u32 v45, v45, 11, v2
	v_lshl_add_u32 v46, v46, 11, v2
	v_lshl_add_u32 v47, v47, 11, v2
	v_lshl_add_u32 v48, v48, 11, v2
	v_lshl_add_u32 v49, v49, 11, v2
	v_lshl_add_u32 v50, v50, 11, v2
	v_lshl_add_u32 v51, v51, 11, v2
	global_load_dwordx4 v[84:87], v20, s[20:21]
	global_load_dwordx4 v[88:91], v21, s[20:21]
	global_load_dwordx4 v[92:95], v22, s[20:21]
	global_load_dwordx4 v[96:99], v23, s[20:21]
	global_load_dwordx4 v[100:103], v24, s[20:21]
	global_load_dwordx4 v[104:107], v25, s[20:21]
	global_load_dwordx4 v[108:111], v26, s[20:21]
	global_load_dwordx4 v[112:115], v27, s[20:21]
	global_load_dwordx4 v[116:119], v28, s[20:21]
	global_load_dwordx4 v[120:123], v29, s[20:21]
	global_load_dwordx4 v[124:127], v30, s[20:21]
	global_load_dwordx4 v[128:131], v31, s[20:21]
	global_load_dwordx4 v[132:135], v32, s[20:21]
	global_load_dwordx4 v[136:139], v33, s[20:21]
	global_load_dwordx4 v[140:143], v34, s[20:21]
	global_load_dwordx4 v[144:147], v35, s[20:21]
	global_load_dwordx4 v[148:151], v36, s[20:21]
	global_load_dwordx4 v[152:155], v37, s[20:21]
	global_load_dwordx4 v[156:159], v38, s[20:21]
	global_load_dwordx4 v[160:163], v39, s[20:21]
	global_load_dwordx4 v[164:167], v40, s[20:21]
	global_load_dwordx4 v[168:171], v41, s[20:21]
	global_load_dwordx4 v[172:175], v42, s[20:21]
	global_load_dwordx4 v[176:179], v43, s[20:21]
	global_load_dwordx4 v[180:183], v44, s[20:21]
	global_load_dwordx4 v[184:187], v45, s[20:21]
	global_load_dwordx4 v[190:193], v46, s[20:21]
	global_load_dwordx4 v[194:197], v47, s[20:21]
	global_load_dwordx4 v[198:201], v48, s[20:21]
	global_load_dwordx4 v[202:205], v49, s[20:21]
	global_load_dwordx4 v[206:209], v50, s[20:21]
	global_load_dwordx4 v[210:213], v51, s[20:21]
	v_mov_b32_e32 v52, 0
	v_mov_b32_e32 v53, 0
	v_mov_b32_e32 v54, 0
	v_mov_b32_e32 v55, 0
	v_mov_b32_e32 v56, 0
	v_mov_b32_e32 v57, 0
	v_mov_b32_e32 v58, 0
	v_mov_b32_e32 v59, 0
	v_mov_b32_e32 v60, 0
	v_mov_b32_e32 v61, 0
	v_mov_b32_e32 v62, 0
	v_mov_b32_e32 v63, 0
	v_mov_b32_e32 v64, 0
	v_mov_b32_e32 v65, 0
	v_mov_b32_e32 v66, 0
	v_mov_b32_e32 v67, 0
	v_mov_b32_e32 v68, 0
	v_mov_b32_e32 v69, 0
	v_mov_b32_e32 v70, 0
	v_mov_b32_e32 v71, 0
	v_mov_b32_e32 v72, 0
	v_mov_b32_e32 v73, 0
	v_mov_b32_e32 v74, 0
	v_mov_b32_e32 v75, 0
	v_mov_b32_e32 v76, 0
	v_mov_b32_e32 v77, 0
	v_mov_b32_e32 v78, 0
	v_mov_b32_e32 v79, 0
	v_mov_b32_e32 v80, 0
	v_mov_b32_e32 v81, 0
	v_mov_b32_e32 v82, 0
	v_mov_b32_e32 v83, 0
	s_waitcnt vmcnt(31)
; DI void wave_lds_sync() { asm volatile("s_waitcnt lgkmcnt(0)" ::: "memory"); __builtin_amdgcn_wave_barrier(); }
; DI void phase9(const Params& p, char* smem, int rep) {
;     ...
;       lw[(lane & 3) * 32 + (lane >> 2)] = i0;
;       lw[(lane & 3) * 32 + 16 + (lane >> 2)] = i1;
;       wave_lds_sync();
;       const unsigned char* ub = U8 + s * 256 + l15 * 16;
; #pragma unroll
;       for (int batch = 0; batch < 2; ++batch) {
;         int ida[16];
; #pragma unroll
;         for (int q = 0; q < 4; ++q) { const int4 v = *(const int4*)(lw + g * 32 + batch * 16 + q * 4); ida[q * 4] = v.x; ida[q * 4 + 1] = v.y; ida[q * 4 + 2] = v.z; ida[q * 4 + 3] = v.w; }
;         u32x4 rows[16];
; #pragma unroll
;         for (int k = 0; k < 16; ++k) rows[k] = *(const u32x4*)(ub + (size_t)ida[k] * 2048);
;         int part[16];
; #pragma unroll
;         for (int k = 0; k < 16; ++k) {
;           int acc = 0;
; #pragma unroll
;           for (int d = 0; d < 4; ++d) acc = __builtin_amdgcn_sdot4((int)rows[k][d], (int)hq[d], acc, false);
;           part[k] = acc;
;         }
;         int q8[8], q4[4], q2[2];
; #pragma unroll
;         for (int k = 0; k < 8; ++k) q8[k] = (b3 ? part[8 + k] : part[k]) + __shfl_xor(b3 ? part[k] : part[8 + k], 8);
; #pragma unroll
;         for (int k = 0; k < 4; ++k) q4[k] = (b2 ? q8[4 + k] : q8[k]) + __shfl_xor(b2 ? q8[k] : q8[4 + k], 4);
; #pragma unroll
;         for (int k = 0; k < 2; ++k) q2[k] = (b1 ? q4[2 + k] : q4[k]) + __shfl_xor(b1 ? q4[k] : q4[2 + k], 2);
;         const int rr = (b0 ? q2[1] : q2[0]) + __shfl_xor(b0 ? q2[0] : q2[1], 1);
;         PA[((size_t)s * T_ + tok) * 128 + 4 * (batch * 16 + l15) + g] = rr;
	v_dot4c_i32_i8_e32 v52, v84, v12
	s_waitcnt vmcnt(30)
	v_dot4c_i32_i8_e32 v53, v88, v12
	s_waitcnt vmcnt(29)
	v_dot4c_i32_i8_e32 v54, v92, v12
	s_waitcnt vmcnt(28)
	v_dot4c_i32_i8_e32 v55, v96, v12
	s_waitcnt vmcnt(27)
	v_dot4c_i32_i8_e32 v56, v100, v12
	s_waitcnt vmcnt(26)
	v_dot4c_i32_i8_e32 v57, v104, v12
	s_waitcnt vmcnt(25)
	v_dot4c_i32_i8_e32 v58, v108, v12
	s_waitcnt vmcnt(24)
	v_dot4c_i32_i8_e32 v59, v112, v12
	s_waitcnt vmcnt(23)
	v_dot4c_i32_i8_e32 v60, v116, v12
	s_waitcnt vmcnt(22)
	v_dot4c_i32_i8_e32 v61, v120, v12
	s_waitcnt vmcnt(21)
	v_dot4c_i32_i8_e32 v62, v124, v12
	s_waitcnt vmcnt(20)
	v_dot4c_i32_i8_e32 v63, v128, v12
	s_waitcnt vmcnt(19)
	v_dot4c_i32_i8_e32 v64, v132, v12
	s_waitcnt vmcnt(18)
	v_dot4c_i32_i8_e32 v65, v136, v12
	s_waitcnt vmcnt(17)
	v_dot4c_i32_i8_e32 v66, v140, v12
	s_waitcnt vmcnt(16)
	v_dot4c_i32_i8_e32 v67, v144, v12
	v_dot4c_i32_i8_e32 v52, v85, v13
	v_dot4c_i32_i8_e32 v53, v89, v13
	v_dot4c_i32_i8_e32 v54, v93, v13
	v_dot4c_i32_i8_e32 v55, v97, v13
	v_dot4c_i32_i8_e32 v56, v101, v13
	v_dot4c_i32_i8_e32 v57, v105, v13
	v_dot4c_i32_i8_e32 v58, v109, v13
	v_dot4c_i32_i8_e32 v59, v113, v13
	v_dot4c_i32_i8_e32 v60, v117, v13
	v_dot4c_i32_i8_e32 v61, v121, v13
	v_dot4c_i32_i8_e32 v62, v125, v13
	v_dot4c_i32_i8_e32 v63, v129, v13
	v_dot4c_i32_i8_e32 v64, v133, v13
	v_dot4c_i32_i8_e32 v65, v137, v13
	v_dot4c_i32_i8_e32 v66, v141, v13
	v_dot4c_i32_i8_e32 v67, v145, v13
	v_dot4c_i32_i8_e32 v52, v86, v14
	v_dot4c_i32_i8_e32 v53, v90, v14
	v_dot4c_i32_i8_e32 v54, v94, v14
	v_dot4c_i32_i8_e32 v55, v98, v14
	v_dot4c_i32_i8_e32 v56, v102, v14
	v_dot4c_i32_i8_e32 v57, v106, v14
	v_dot4c_i32_i8_e32 v58, v110, v14
	v_dot4c_i32_i8_e32 v59, v114, v14
	v_dot4c_i32_i8_e32 v60, v118, v14
	v_dot4c_i32_i8_e32 v61, v122, v14
	v_dot4c_i32_i8_e32 v62, v126, v14
	v_dot4c_i32_i8_e32 v63, v130, v14
	v_dot4c_i32_i8_e32 v64, v134, v14
	v_dot4c_i32_i8_e32 v65, v138, v14
	v_dot4c_i32_i8_e32 v66, v142, v14
	v_dot4c_i32_i8_e32 v67, v146, v14
	v_dot4c_i32_i8_e32 v52, v87, v15
	v_dot4c_i32_i8_e32 v53, v91, v15
	v_dot4c_i32_i8_e32 v54, v95, v15
	v_dot4c_i32_i8_e32 v55, v99, v15
	v_dot4c_i32_i8_e32 v56, v103, v15
	v_dot4c_i32_i8_e32 v57, v107, v15
	v_dot4c_i32_i8_e32 v58, v111, v15
	v_dot4c_i32_i8_e32 v59, v115, v15
	v_dot4c_i32_i8_e32 v60, v119, v15
	v_dot4c_i32_i8_e32 v61, v123, v15
	v_dot4c_i32_i8_e32 v62, v127, v15
	v_dot4c_i32_i8_e32 v63, v131, v15
	v_dot4c_i32_i8_e32 v64, v135, v15
	v_dot4c_i32_i8_e32 v65, v139, v15
	v_dot4c_i32_i8_e32 v66, v143, v15
	v_dot4c_i32_i8_e32 v67, v147, v15
	ds_write2_b32 v5, v10, v11 offset0:4 offset1:20
	s_waitcnt lgkmcnt(0)
	ds_read_b128 v[20:23], v6 offset:16
	ds_read_b128 v[24:27], v6 offset:32
	ds_read_b128 v[28:31], v6 offset:48
	ds_read_b128 v[32:35], v6 offset:64
	ds_read_b128 v[36:39], v6 offset:80
	ds_read_b128 v[40:43], v6 offset:96
	ds_read_b128 v[44:47], v6 offset:112
	ds_read_b128 v[48:51], v6 offset:128
	v_add_u32_dpp v84, v52, v52 row_ror:8 row_mask:0xf bank_mask:0x3
	v_add_u32_dpp v84, v60, v60 row_ror:8 row_mask:0xf bank_mask:0xc
	v_add_u32_dpp v85, v53, v53 row_ror:8 row_mask:0xf bank_mask:0x3
	v_add_u32_dpp v85, v61, v61 row_ror:8 row_mask:0xf bank_mask:0xc
	v_add_u32_dpp v86, v54, v54 row_ror:8 row_mask:0xf bank_mask:0x3
	v_add_u32_dpp v86, v62, v62 row_ror:8 row_mask:0xf bank_mask:0xc
	v_add_u32_dpp v87, v55, v55 row_ror:8 row_mask:0xf bank_mask:0x3
	v_add_u32_dpp v87, v63, v63 row_ror:8 row_mask:0xf bank_mask:0xc
	v_add_u32_dpp v88, v56, v56 row_ror:8 row_mask:0xf bank_mask:0x3
	v_add_u32_dpp v88, v64, v64 row_ror:8 row_mask:0xf bank_mask:0xc
	v_add_u32_dpp v89, v57, v57 row_ror:8 row_mask:0xf bank_mask:0x3
	v_add_u32_dpp v89, v65, v65 row_ror:8 row_mask:0xf bank_mask:0xc
	v_add_u32_dpp v90, v58, v58 row_ror:8 row_mask:0xf bank_mask:0x3
	v_add_u32_dpp v90, v66, v66 row_ror:8 row_mask:0xf bank_mask:0xc
	v_add_u32_dpp v91, v59, v59 row_ror:8 row_mask:0xf bank_mask:0x3
	v_add_u32_dpp v91, v67, v67 row_ror:8 row_mask:0xf bank_mask:0xc
	v_add_u32_dpp v92, v84, v84 row_half_mirror row_mask:0xf bank_mask:0x5
	v_add_u32_dpp v92, v88, v88 row_half_mirror row_mask:0xf bank_mask:0xa
	v_add_u32_dpp v93, v85, v85 row_half_mirror row_mask:0xf bank_mask:0x5
	v_add_u32_dpp v93, v89, v89 row_half_mirror row_mask:0xf bank_mask:0xa
	v_add_u32_dpp v94, v86, v86 row_half_mirror row_mask:0xf bank_mask:0x5
	v_add_u32_dpp v94, v90, v90 row_half_mirror row_mask:0xf bank_mask:0xa
	v_add_u32_dpp v95, v87, v87 row_half_mirror row_mask:0xf bank_mask:0x5
	v_add_u32_dpp v95, v91, v91 row_half_mirror row_mask:0xf bank_mask:0xa
	v_add_u32_dpp v96, v92, v92 quad_perm:[2,3,0,1] row_mask:0xf bank_mask:0xf
	v_add_u32_dpp v97, v93, v93 quad_perm:[2,3,0,1] row_mask:0xf bank_mask:0xf
	v_add_u32_dpp v98, v94, v94 quad_perm:[2,3,0,1] row_mask:0xf bank_mask:0xf
	s_nop 0
	v_add_u32_dpp v99, v95, v95 quad_perm:[2,3,0,1] row_mask:0xf bank_mask:0xf
	v_cndmask_b32_e64 v100, v98, v96, s[2:3]
	v_cndmask_b32_e64 v101, v99, v97, s[2:3]
	v_add_u32_e32 v214, s46, v4
	s_nop 1
	v_add_u32_dpp v102, v100, v100 quad_perm:[1,0,3,2] row_mask:0xf bank_mask:0xf
	v_add_u32_dpp v103, v101, v101 quad_perm:[1,0,3,2] row_mask:0xf bank_mask:0xf
	v_cndmask_b32_e64 v104, v103, v102, s[4:5]
	global_store_dword v214, v104, s[14:15]
	s_waitcnt vmcnt(16)
	v_dot4c_i32_i8_e32 v68, v148, v12
	s_waitcnt vmcnt(15)
	v_dot4c_i32_i8_e32 v69, v152, v12
	s_waitcnt vmcnt(14)
	v_dot4c_i32_i8_e32 v70, v156, v12
	s_waitcnt vmcnt(13)
	v_dot4c_i32_i8_e32 v71, v160, v12
	s_waitcnt vmcnt(12)
	v_dot4c_i32_i8_e32 v72, v164, v12
	s_waitcnt vmcnt(11)
	v_dot4c_i32_i8_e32 v73, v168, v12
	s_waitcnt vmcnt(10)
	v_dot4c_i32_i8_e32 v74, v172, v12
	s_waitcnt vmcnt(9)
; DI void wave_lds_sync() { asm volatile("s_waitcnt lgkmcnt(0)" ::: "memory"); __builtin_amdgcn_wave_barrier(); }
; DI void phase9(const Params& p, char* smem, int rep) {
;     ...
;       const int tok = __builtin_amdgcn_readfirstlane(c * 16 + w * 4 + t);
;       const int i0 = IDS[(size_t)tok * 128 + lane], i1 = IDS[(size_t)tok * 128 + 64 + lane];
;       const u32x4 hq = *(const u32x4*)(H2Q + (size_t)tok * D_ + s * 256 + l15 * 16);
;       wave_lds_sync();
;       lw[(lane & 3) * 32 + (lane >> 2)] = i0;
;       lw[(lane & 3) * 32 + 16 + (lane >> 2)] = i1;
;       wave_lds_sync();
;       const unsigned char* ub = U8 + s * 256 + l15 * 16;
; #pragma unroll
;       for (int batch = 0; batch < 2; ++batch) {
;         int ida[16];
; #pragma unroll
;         for (int q = 0; q < 4; ++q) { const int4 v = *(const int4*)(lw + g * 32 + batch * 16 + q * 4); ida[q * 4] = v.x; ida[q * 4 + 1] = v.y; ida[q * 4 + 2] = v.z; ida[q * 4 + 3] = v.w; }
;         u32x4 rows[16];
; #pragma unroll
;         for (int k = 0; k < 16; ++k) rows[k] = *(const u32x4*)(ub + (size_t)ida[k] * 2048);
;         int part[16];
; #pragma unroll
;         for (int k = 0; k < 16; ++k) {
;           int acc = 0;
; #pragma unroll
;           for (int d = 0; d < 4; ++d) acc = __builtin_amdgcn_sdot4((int)rows[k][d], (int)hq[d], acc, false);
;           part[k] = acc;
;         }
;         int q8[8], q4[4], q2[2];
; #pragma unroll
;         for (int k = 0; k < 8; ++k) q8[k] = (b3 ? part[8 + k] : part[k]) + __shfl_xor(b3 ? part[k] : part[8 + k], 8);
; #pragma unroll
;         for (int k = 0; k < 4; ++k) q4[k] = (b2 ? q8[4 + k] : q8[k]) + __shfl_xor(b2 ? q8[k] : q8[4 + k], 4);
; #pragma unroll
;         for (int k = 0; k < 2; ++k) q2[k] = (b1 ? q4[2 + k] : q4[k]) + __shfl_xor(b1 ? q4[k] : q4[2 + k], 2);
;         const int rr = (b0 ? q2[1] : q2[0]) + __shfl_xor(b0 ? q2[0] : q2[1], 1);
;         PA[((size_t)s * T_ + tok) * 128 + 4 * (batch * 16 + l15) + g] = rr;
	v_dot4c_i32_i8_e32 v75, v176, v12
	s_waitcnt vmcnt(8)
	v_dot4c_i32_i8_e32 v76, v180, v12
	s_waitcnt vmcnt(7)
	v_dot4c_i32_i8_e32 v77, v184, v12
	s_waitcnt vmcnt(6)
	v_dot4c_i32_i8_e32 v78, v190, v12
	s_waitcnt vmcnt(5)
	v_dot4c_i32_i8_e32 v79, v194, v12
	s_waitcnt vmcnt(4)
	v_dot4c_i32_i8_e32 v80, v198, v12
	s_waitcnt vmcnt(3)
	v_dot4c_i32_i8_e32 v81, v202, v12
	s_waitcnt vmcnt(2)
	v_dot4c_i32_i8_e32 v82, v206, v12
	s_waitcnt vmcnt(1)
	v_dot4c_i32_i8_e32 v83, v210, v12
	v_dot4c_i32_i8_e32 v68, v149, v13
	v_dot4c_i32_i8_e32 v69, v153, v13
	v_dot4c_i32_i8_e32 v70, v157, v13
	v_dot4c_i32_i8_e32 v71, v161, v13
	v_dot4c_i32_i8_e32 v72, v165, v13
	v_dot4c_i32_i8_e32 v73, v169, v13
	v_dot4c_i32_i8_e32 v74, v173, v13
	v_dot4c_i32_i8_e32 v75, v177, v13
	v_dot4c_i32_i8_e32 v76, v181, v13
	v_dot4c_i32_i8_e32 v77, v185, v13
	v_dot4c_i32_i8_e32 v78, v191, v13
	v_dot4c_i32_i8_e32 v79, v195, v13
	v_dot4c_i32_i8_e32 v80, v199, v13
	v_dot4c_i32_i8_e32 v81, v203, v13
	v_dot4c_i32_i8_e32 v82, v207, v13
	v_dot4c_i32_i8_e32 v83, v211, v13
	v_dot4c_i32_i8_e32 v68, v150, v14
	v_dot4c_i32_i8_e32 v69, v154, v14
	v_dot4c_i32_i8_e32 v70, v158, v14
	v_dot4c_i32_i8_e32 v71, v162, v14
	v_dot4c_i32_i8_e32 v72, v166, v14
	v_dot4c_i32_i8_e32 v73, v170, v14
	v_dot4c_i32_i8_e32 v74, v174, v14
	v_dot4c_i32_i8_e32 v75, v178, v14
	v_dot4c_i32_i8_e32 v76, v182, v14
	v_dot4c_i32_i8_e32 v77, v186, v14
	v_dot4c_i32_i8_e32 v78, v192, v14
	v_dot4c_i32_i8_e32 v79, v196, v14
	v_dot4c_i32_i8_e32 v80, v200, v14
	v_dot4c_i32_i8_e32 v81, v204, v14
	v_dot4c_i32_i8_e32 v82, v208, v14
	v_dot4c_i32_i8_e32 v83, v212, v14
	v_dot4c_i32_i8_e32 v68, v151, v15
	v_dot4c_i32_i8_e32 v69, v155, v15
	v_dot4c_i32_i8_e32 v70, v159, v15
	v_dot4c_i32_i8_e32 v71, v163, v15
	v_dot4c_i32_i8_e32 v72, v167, v15
	v_dot4c_i32_i8_e32 v73, v171, v15
	v_dot4c_i32_i8_e32 v74, v175, v15
	v_dot4c_i32_i8_e32 v75, v179, v15
	v_dot4c_i32_i8_e32 v76, v183, v15
	v_dot4c_i32_i8_e32 v77, v187, v15
	v_dot4c_i32_i8_e32 v78, v193, v15
	v_dot4c_i32_i8_e32 v79, v197, v15
	v_dot4c_i32_i8_e32 v80, v201, v15
	v_dot4c_i32_i8_e32 v81, v205, v15
	v_dot4c_i32_i8_e32 v82, v209, v15
	v_dot4c_i32_i8_e32 v83, v213, v15
	v_add_u32_dpp v148, v68, v68 row_ror:8 row_mask:0xf bank_mask:0x3
	v_add_u32_dpp v148, v76, v76 row_ror:8 row_mask:0xf bank_mask:0xc
	v_add_u32_dpp v149, v69, v69 row_ror:8 row_mask:0xf bank_mask:0x3
	v_add_u32_dpp v149, v77, v77 row_ror:8 row_mask:0xf bank_mask:0xc
	v_add_u32_dpp v150, v70, v70 row_ror:8 row_mask:0xf bank_mask:0x3
	v_add_u32_dpp v150, v78, v78 row_ror:8 row_mask:0xf bank_mask:0xc
	v_add_u32_dpp v151, v71, v71 row_ror:8 row_mask:0xf bank_mask:0x3
	v_add_u32_dpp v151, v79, v79 row_ror:8 row_mask:0xf bank_mask:0xc
	v_add_u32_dpp v152, v72, v72 row_ror:8 row_mask:0xf bank_mask:0x3
	v_add_u32_dpp v152, v80, v80 row_ror:8 row_mask:0xf bank_mask:0xc
	v_add_u32_dpp v153, v73, v73 row_ror:8 row_mask:0xf bank_mask:0x3
	v_add_u32_dpp v153, v81, v81 row_ror:8 row_mask:0xf bank_mask:0xc
	v_add_u32_dpp v154, v74, v74 row_ror:8 row_mask:0xf bank_mask:0x3
	v_add_u32_dpp v154, v82, v82 row_ror:8 row_mask:0xf bank_mask:0xc
	v_add_u32_dpp v155, v75, v75 row_ror:8 row_mask:0xf bank_mask:0x3
	v_add_u32_dpp v155, v83, v83 row_ror:8 row_mask:0xf bank_mask:0xc
	v_add_u32_dpp v156, v148, v148 row_half_mirror row_mask:0xf bank_mask:0x5
	v_add_u32_dpp v156, v152, v152 row_half_mirror row_mask:0xf bank_mask:0xa
	v_add_u32_dpp v157, v149, v149 row_half_mirror row_mask:0xf bank_mask:0x5
	v_add_u32_dpp v157, v153, v153 row_half_mirror row_mask:0xf bank_mask:0xa
	v_add_u32_dpp v158, v150, v150 row_half_mirror row_mask:0xf bank_mask:0x5
	v_add_u32_dpp v158, v154, v154 row_half_mirror row_mask:0xf bank_mask:0xa
	v_add_u32_dpp v159, v151, v151 row_half_mirror row_mask:0xf bank_mask:0x5
	v_add_u32_dpp v159, v155, v155 row_half_mirror row_mask:0xf bank_mask:0xa
	v_add_u32_dpp v160, v156, v156 quad_perm:[2,3,0,1] row_mask:0xf bank_mask:0xf
	v_add_u32_dpp v161, v157, v157 quad_perm:[2,3,0,1] row_mask:0xf bank_mask:0xf
	v_add_u32_dpp v162, v158, v158 quad_perm:[2,3,0,1] row_mask:0xf bank_mask:0xf
	s_nop 0
	v_add_u32_dpp v163, v159, v159 quad_perm:[2,3,0,1] row_mask:0xf bank_mask:0xf
	v_cndmask_b32_e64 v164, v162, v160, s[2:3]
	v_cndmask_b32_e64 v165, v163, v161, s[2:3]
	s_nop 0
	s_nop 1
	v_add_u32_dpp v166, v164, v164 quad_perm:[1,0,3,2] row_mask:0xf bank_mask:0xf
	v_add_u32_dpp v167, v165, v165 quad_perm:[1,0,3,2] row_mask:0xf bank_mask:0xf
	v_cndmask_b32_e64 v168, v167, v166, s[4:5]
	global_store_dword v214, v168, s[14:15] offset:256
	s_add_i32 s36, s34, 1
	s_lshl_b32 s46, s36, 9
	s_add_i32 s46, s46, s24
	s_add_i32 s37, s34, 2
	s_lshl_b32 s47, s37, 9
	s_add_u32 s42, s6, s47
	s_addc_u32 s43, s7, 0
	s_lshl_b32 s47, s37, 11
	s_add_u32 s44, s22, s47
	s_addc_u32 s45, s23, 0
	global_load_dword v10, v3, s[42:43]
	global_load_dword v11, v3, s[42:43] offset:256
	global_load_dwordx4 v[12:15], v2, s[44:45]
	s_waitcnt lgkmcnt(0)
; DI void wave_lds_sync() { asm volatile("s_waitcnt lgkmcnt(0)" ::: "memory"); __builtin_amdgcn_wave_barrier(); }
; DI void phase9(const Params& p, char* smem, int rep) {
;     ...
;       const int tok = __builtin_amdgcn_readfirstlane(c * 16 + w * 4 + t);
;       const int i0 = IDS[(size_t)tok * 128 + lane], i1 = IDS[(size_t)tok * 128 + 64 + lane];
;       const u32x4 hq = *(const u32x4*)(H2Q + (size_t)tok * D_ + s * 256 + l15 * 16);
;       wave_lds_sync();
;       lw[(lane & 3) * 32 + (lane >> 2)] = i0;
;       lw[(lane & 3) * 32 + 16 + (lane >> 2)] = i1;
;       wave_lds_sync();
;       const unsigned char* ub = U8 + s * 256 + l15 * 16;
; #pragma unroll
;       for (int batch = 0; batch < 2; ++batch) {
;         int ida[16];
; #pragma unroll
;         for (int q = 0; q < 4; ++q) { const int4 v = *(const int4*)(lw + g * 32 + batch * 16 + q * 4); ida[q * 4] = v.x; ida[q * 4 + 1] = v.y; ida[q * 4 + 2] = v.z; ida[q * 4 + 3] = v.w; }
;         u32x4 rows[16];
; #pragma unroll
;         for (int k = 0; k < 16; ++k) rows[k] = *(const u32x4*)(ub + (size_t)ida[k] * 2048);
;         int part[16];
; #pragma unroll
;         for (int k = 0; k < 16; ++k) {
;           int acc = 0;
; #pragma unroll
;           for (int d = 0; d < 4; ++d) acc = __builtin_amdgcn_sdot4((int)rows[k][d], (int)hq[d], acc, false);
;           part[k] = acc;
;         }
;         int q8[8], q4[4], q2[2];
; #pragma unroll
;         for (int k = 0; k < 8; ++k) q8[k] = (b3 ? part[8 + k] : part[k]) + __shfl_xor(b3 ? part[k] : part[8 + k], 8);
; #pragma unroll
;         for (int k = 0; k < 4; ++k) q4[k] = (b2 ? q8[4 + k] : q8[k]) + __shfl_xor(b2 ? q8[k] : q8[4 + k], 4);
; #pragma unroll
;         for (int k = 0; k < 2; ++k) q2[k] = (b1 ? q4[2 + k] : q4[k]) + __shfl_xor(b1 ? q4[k] : q4[2 + k], 2);
;         const int rr = (b0 ? q2[1] : q2[0]) + __shfl_xor(b0 ? q2[0] : q2[1], 1);
;         PA[((size_t)s * T_ + tok) * 128 + 4 * (batch * 16 + l15) + g] = rr;
	v_lshl_add_u32 v20, v20, 11, v2
	v_lshl_add_u32 v21, v21, 11, v2
	v_lshl_add_u32 v22, v22, 11, v2
	v_lshl_add_u32 v23, v23, 11, v2
	v_lshl_add_u32 v24, v24, 11, v2
	v_lshl_add_u32 v25, v25, 11, v2
	v_lshl_add_u32 v26, v26, 11, v2
	v_lshl_add_u32 v27, v27, 11, v2
	v_lshl_add_u32 v28, v28, 11, v2
	v_lshl_add_u32 v29, v29, 11, v2
	v_lshl_add_u32 v30, v30, 11, v2
	v_lshl_add_u32 v31, v31, 11, v2
	v_lshl_add_u32 v32, v32, 11, v2
	v_lshl_add_u32 v33, v33, 11, v2
	v_lshl_add_u32 v34, v34, 11, v2
	v_lshl_add_u32 v35, v35, 11, v2
	v_lshl_add_u32 v36, v36, 11, v2
	v_lshl_add_u32 v37, v37, 11, v2
	v_lshl_add_u32 v38, v38, 11, v2
	v_lshl_add_u32 v39, v39, 11, v2
	v_lshl_add_u32 v40, v40, 11, v2
	v_lshl_add_u32 v41, v41, 11, v2
	v_lshl_add_u32 v42, v42, 11, v2
	v_lshl_add_u32 v43, v43, 11, v2
	v_lshl_add_u32 v44, v44, 11, v2
	v_lshl_add_u32 v45, v45, 11, v2
	v_lshl_add_u32 v46, v46, 11, v2
	v_lshl_add_u32 v47, v47, 11, v2
	v_lshl_add_u32 v48, v48, 11, v2
	v_lshl_add_u32 v49, v49, 11, v2
	v_lshl_add_u32 v50, v50, 11, v2
	v_lshl_add_u32 v51, v51, 11, v2
	global_load_dwordx4 v[84:87], v20, s[20:21]
	global_load_dwordx4 v[88:91], v21, s[20:21]
	global_load_dwordx4 v[92:95], v22, s[20:21]
	global_load_dwordx4 v[96:99], v23, s[20:21]
	global_load_dwordx4 v[100:103], v24, s[20:21]
	global_load_dwordx4 v[104:107], v25, s[20:21]
	global_load_dwordx4 v[108:111], v26, s[20:21]
	global_load_dwordx4 v[112:115], v27, s[20:21]
	global_load_dwordx4 v[116:119], v28, s[20:21]
	global_load_dwordx4 v[120:123], v29, s[20:21]
	global_load_dwordx4 v[124:127], v30, s[20:21]
	global_load_dwordx4 v[128:131], v31, s[20:21]
	global_load_dwordx4 v[132:135], v32, s[20:21]
	global_load_dwordx4 v[136:139], v33, s[20:21]
	global_load_dwordx4 v[140:143], v34, s[20:21]
	global_load_dwordx4 v[144:147], v35, s[20:21]
	global_load_dwordx4 v[148:151], v36, s[20:21]
	global_load_dwordx4 v[152:155], v37, s[20:21]
	global_load_dwordx4 v[156:159], v38, s[20:21]
	global_load_dwordx4 v[160:163], v39, s[20:21]
	global_load_dwordx4 v[164:167], v40, s[20:21]
	global_load_dwordx4 v[168:171], v41, s[20:21]
	global_load_dwordx4 v[172:175], v42, s[20:21]
	global_load_dwordx4 v[176:179], v43, s[20:21]
	global_load_dwordx4 v[180:183], v44, s[20:21]
	global_load_dwordx4 v[184:187], v45, s[20:21]
	global_load_dwordx4 v[190:193], v46, s[20:21]
	global_load_dwordx4 v[194:197], v47, s[20:21]
	global_load_dwordx4 v[198:201], v48, s[20:21]
	global_load_dwordx4 v[202:205], v49, s[20:21]
	global_load_dwordx4 v[206:209], v50, s[20:21]
	global_load_dwordx4 v[210:213], v51, s[20:21]
	v_mov_b32_e32 v52, 0
	v_mov_b32_e32 v53, 0
	v_mov_b32_e32 v54, 0
	v_mov_b32_e32 v55, 0
	v_mov_b32_e32 v56, 0
	v_mov_b32_e32 v57, 0
	v_mov_b32_e32 v58, 0
	v_mov_b32_e32 v59, 0
	v_mov_b32_e32 v60, 0
	v_mov_b32_e32 v61, 0
	v_mov_b32_e32 v62, 0
	v_mov_b32_e32 v63, 0
	v_mov_b32_e32 v64, 0
	v_mov_b32_e32 v65, 0
	v_mov_b32_e32 v66, 0
	v_mov_b32_e32 v67, 0
	v_mov_b32_e32 v68, 0
	v_mov_b32_e32 v69, 0
	v_mov_b32_e32 v70, 0
	v_mov_b32_e32 v71, 0
	v_mov_b32_e32 v72, 0
	v_mov_b32_e32 v73, 0
	v_mov_b32_e32 v74, 0
	v_mov_b32_e32 v75, 0
	v_mov_b32_e32 v76, 0
	v_mov_b32_e32 v77, 0
	v_mov_b32_e32 v78, 0
	v_mov_b32_e32 v79, 0
	v_mov_b32_e32 v80, 0
	v_mov_b32_e32 v81, 0
	v_mov_b32_e32 v82, 0
	v_mov_b32_e32 v83, 0
	s_waitcnt vmcnt(31)
	v_dot4c_i32_i8_e32 v52, v84, v16
	s_waitcnt vmcnt(30)
	v_dot4c_i32_i8_e32 v53, v88, v16
	s_waitcnt vmcnt(29)
	v_dot4c_i32_i8_e32 v54, v92, v16
	s_waitcnt vmcnt(28)
	v_dot4c_i32_i8_e32 v55, v96, v16
	s_waitcnt vmcnt(27)
	v_dot4c_i32_i8_e32 v56, v100, v16
	s_waitcnt vmcnt(26)
	v_dot4c_i32_i8_e32 v57, v104, v16
	s_waitcnt vmcnt(25)
	v_dot4c_i32_i8_e32 v58, v108, v16
	s_waitcnt vmcnt(24)
	v_dot4c_i32_i8_e32 v59, v112, v16
	s_waitcnt vmcnt(23)
	v_dot4c_i32_i8_e32 v60, v116, v16
	s_waitcnt vmcnt(22)
	v_dot4c_i32_i8_e32 v61, v120, v16
	s_waitcnt vmcnt(21)
	v_dot4c_i32_i8_e32 v62, v124, v16
	s_waitcnt vmcnt(20)
	v_dot4c_i32_i8_e32 v63, v128, v16
	s_waitcnt vmcnt(19)
	v_dot4c_i32_i8_e32 v64, v132, v16
	s_waitcnt vmcnt(18)
	v_dot4c_i32_i8_e32 v65, v136, v16
	s_waitcnt vmcnt(17)
	v_dot4c_i32_i8_e32 v66, v140, v16
	s_waitcnt vmcnt(16)
	v_dot4c_i32_i8_e32 v67, v144, v16
	v_dot4c_i32_i8_e32 v52, v85, v17
	v_dot4c_i32_i8_e32 v53, v89, v17
	v_dot4c_i32_i8_e32 v54, v93, v17
	v_dot4c_i32_i8_e32 v55, v97, v17
	v_dot4c_i32_i8_e32 v56, v101, v17
	v_dot4c_i32_i8_e32 v57, v105, v17
	v_dot4c_i32_i8_e32 v58, v109, v17
	v_dot4c_i32_i8_e32 v59, v113, v17
	v_dot4c_i32_i8_e32 v60, v117, v17
	v_dot4c_i32_i8_e32 v61, v121, v17
	v_dot4c_i32_i8_e32 v62, v125, v17
	v_dot4c_i32_i8_e32 v63, v129, v17
	v_dot4c_i32_i8_e32 v64, v133, v17
	v_dot4c_i32_i8_e32 v65, v137, v17
	v_dot4c_i32_i8_e32 v66, v141, v17
	v_dot4c_i32_i8_e32 v67, v145, v17
	v_dot4c_i32_i8_e32 v52, v86, v18
	v_dot4c_i32_i8_e32 v53, v90, v18
	v_dot4c_i32_i8_e32 v54, v94, v18
	v_dot4c_i32_i8_e32 v55, v98, v18
	v_dot4c_i32_i8_e32 v56, v102, v18
	v_dot4c_i32_i8_e32 v57, v106, v18
	v_dot4c_i32_i8_e32 v58, v110, v18
	v_dot4c_i32_i8_e32 v59, v114, v18
	v_dot4c_i32_i8_e32 v60, v118, v18
	v_dot4c_i32_i8_e32 v61, v122, v18
	v_dot4c_i32_i8_e32 v62, v126, v18
	v_dot4c_i32_i8_e32 v63, v130, v18
	v_dot4c_i32_i8_e32 v64, v134, v18
	v_dot4c_i32_i8_e32 v65, v138, v18
	v_dot4c_i32_i8_e32 v66, v142, v18
	v_dot4c_i32_i8_e32 v67, v146, v18
	v_dot4c_i32_i8_e32 v52, v87, v19
	v_dot4c_i32_i8_e32 v53, v91, v19
	v_dot4c_i32_i8_e32 v54, v95, v19
	v_dot4c_i32_i8_e32 v55, v99, v19
	v_dot4c_i32_i8_e32 v56, v103, v19
	v_dot4c_i32_i8_e32 v57, v107, v19
	v_dot4c_i32_i8_e32 v58, v111, v19
	v_dot4c_i32_i8_e32 v59, v115, v19
	v_dot4c_i32_i8_e32 v60, v119, v19
	v_dot4c_i32_i8_e32 v61, v123, v19
	v_dot4c_i32_i8_e32 v62, v127, v19
	v_dot4c_i32_i8_e32 v63, v131, v19
	v_dot4c_i32_i8_e32 v64, v135, v19
	v_dot4c_i32_i8_e32 v65, v139, v19
	v_dot4c_i32_i8_e32 v66, v143, v19
	v_dot4c_i32_i8_e32 v67, v147, v19
	ds_write2_b32 v5, v10, v11 offset0:4 offset1:20
	s_waitcnt lgkmcnt(0)
; DI void wave_lds_sync() { asm volatile("s_waitcnt lgkmcnt(0)" ::: "memory"); __builtin_amdgcn_wave_barrier(); }
; DI void phase9(const Params& p, char* smem, int rep) {
;     ...
;       const int tok = __builtin_amdgcn_readfirstlane(c * 16 + w * 4 + t);
;       const int i0 = IDS[(size_t)tok * 128 + lane], i1 = IDS[(size_t)tok * 128 + 64 + lane];
;       const u32x4 hq = *(const u32x4*)(H2Q + (size_t)tok * D_ + s * 256 + l15 * 16);
;       wave_lds_sync();
;       lw[(lane & 3) * 32 + (lane >> 2)] = i0;
;       lw[(lane & 3) * 32 + 16 + (lane >> 2)] = i1;
;       wave_lds_sync();
;       const unsigned char* ub = U8 + s * 256 + l15 * 16;
; #pragma unroll
;       for (int batch = 0; batch < 2; ++batch) {
;         int ida[16];
; #pragma unroll
;         for (int q = 0; q < 4; ++q) { const int4 v = *(const int4*)(lw + g * 32 + batch * 16 + q * 4); ida[q * 4] = v.x; ida[q * 4 + 1] = v.y; ida[q * 4 + 2] = v.z; ida[q * 4 + 3] = v.w; }
;         u32x4 rows[16];
; #pragma unroll
;         for (int k = 0; k < 16; ++k) rows[k] = *(const u32x4*)(ub + (size_t)ida[k] * 2048);
;         int part[16];
; #pragma unroll
;         for (int k = 0; k < 16; ++k) {
;           int acc = 0;
; #pragma unroll
;           for (int d = 0; d < 4; ++d) acc = __builtin_amdgcn_sdot4((int)rows[k][d], (int)hq[d], acc, false);
;           part[k] = acc;
;         }
;         int q8[8], q4[4], q2[2];
; #pragma unroll
;         for (int k = 0; k < 8; ++k) q8[k] = (b3 ? part[8 + k] : part[k]) + __shfl_xor(b3 ? part[k] : part[8 + k], 8);
; #pragma unroll
;         for (int k = 0; k < 4; ++k) q4[k] = (b2 ? q8[4 + k] : q8[k]) + __shfl_xor(b2 ? q8[k] : q8[4 + k], 4);
; #pragma unroll
;         for (int k = 0; k < 2; ++k) q2[k] = (b1 ? q4[2 + k] : q4[k]) + __shfl_xor(b1 ? q4[k] : q4[2 + k], 2);
;         const int rr = (b0 ? q2[1] : q2[0]) + __shfl_xor(b0 ? q2[0] : q2[1], 1);
;         PA[((size_t)s * T_ + tok) * 128 + 4 * (batch * 16 + l15) + g] = rr;
	ds_read_b128 v[20:23], v6 offset:16
	ds_read_b128 v[24:27], v6 offset:32
	ds_read_b128 v[28:31], v6 offset:48
	ds_read_b128 v[32:35], v6 offset:64
	ds_read_b128 v[36:39], v6 offset:80
	ds_read_b128 v[40:43], v6 offset:96
	ds_read_b128 v[44:47], v6 offset:112
	ds_read_b128 v[48:51], v6 offset:128
	v_add_u32_dpp v84, v52, v52 row_ror:8 row_mask:0xf bank_mask:0x3
	v_add_u32_dpp v84, v60, v60 row_ror:8 row_mask:0xf bank_mask:0xc
	v_add_u32_dpp v85, v53, v53 row_ror:8 row_mask:0xf bank_mask:0x3
	v_add_u32_dpp v85, v61, v61 row_ror:8 row_mask:0xf bank_mask:0xc
	v_add_u32_dpp v86, v54, v54 row_ror:8 row_mask:0xf bank_mask:0x3
	v_add_u32_dpp v86, v62, v62 row_ror:8 row_mask:0xf bank_mask:0xc
	v_add_u32_dpp v87, v55, v55 row_ror:8 row_mask:0xf bank_mask:0x3
	v_add_u32_dpp v87, v63, v63 row_ror:8 row_mask:0xf bank_mask:0xc
	v_add_u32_dpp v88, v56, v56 row_ror:8 row_mask:0xf bank_mask:0x3
	v_add_u32_dpp v88, v64, v64 row_ror:8 row_mask:0xf bank_mask:0xc
	v_add_u32_dpp v89, v57, v57 row_ror:8 row_mask:0xf bank_mask:0x3
	v_add_u32_dpp v89, v65, v65 row_ror:8 row_mask:0xf bank_mask:0xc
	v_add_u32_dpp v90, v58, v58 row_ror:8 row_mask:0xf bank_mask:0x3
	v_add_u32_dpp v90, v66, v66 row_ror:8 row_mask:0xf bank_mask:0xc
	v_add_u32_dpp v91, v59, v59 row_ror:8 row_mask:0xf bank_mask:0x3
	v_add_u32_dpp v91, v67, v67 row_ror:8 row_mask:0xf bank_mask:0xc
	v_add_u32_dpp v92, v84, v84 row_half_mirror row_mask:0xf bank_mask:0x5
	v_add_u32_dpp v92, v88, v88 row_half_mirror row_mask:0xf bank_mask:0xa
	v_add_u32_dpp v93, v85, v85 row_half_mirror row_mask:0xf bank_mask:0x5
	v_add_u32_dpp v93, v89, v89 row_half_mirror row_mask:0xf bank_mask:0xa
	v_add_u32_dpp v94, v86, v86 row_half_mirror row_mask:0xf bank_mask:0x5
	v_add_u32_dpp v94, v90, v90 row_half_mirror row_mask:0xf bank_mask:0xa
	v_add_u32_dpp v95, v87, v87 row_half_mirror row_mask:0xf bank_mask:0x5
	v_add_u32_dpp v95, v91, v91 row_half_mirror row_mask:0xf bank_mask:0xa
	v_add_u32_dpp v96, v92, v92 quad_perm:[2,3,0,1] row_mask:0xf bank_mask:0xf
	v_add_u32_dpp v97, v93, v93 quad_perm:[2,3,0,1] row_mask:0xf bank_mask:0xf
	v_add_u32_dpp v98, v94, v94 quad_perm:[2,3,0,1] row_mask:0xf bank_mask:0xf
	s_nop 0
	v_add_u32_dpp v99, v95, v95 quad_perm:[2,3,0,1] row_mask:0xf bank_mask:0xf
	v_cndmask_b32_e64 v100, v98, v96, s[2:3]
	v_cndmask_b32_e64 v101, v99, v97, s[2:3]
	v_add_u32_e32 v214, s46, v4
	s_nop 1
	v_add_u32_dpp v102, v100, v100 quad_perm:[1,0,3,2] row_mask:0xf bank_mask:0xf
	v_add_u32_dpp v103, v101, v101 quad_perm:[1,0,3,2] row_mask:0xf bank_mask:0xf
	v_cndmask_b32_e64 v104, v103, v102, s[4:5]
	global_store_dword v214, v104, s[14:15]
	s_waitcnt vmcnt(16)
	v_dot4c_i32_i8_e32 v68, v148, v16
	s_waitcnt vmcnt(15)
	v_dot4c_i32_i8_e32 v69, v152, v16
	s_waitcnt vmcnt(14)
	v_dot4c_i32_i8_e32 v70, v156, v16
	s_waitcnt vmcnt(13)
	v_dot4c_i32_i8_e32 v71, v160, v16
	s_waitcnt vmcnt(12)
	v_dot4c_i32_i8_e32 v72, v164, v16
	s_waitcnt vmcnt(11)
	v_dot4c_i32_i8_e32 v73, v168, v16
	s_waitcnt vmcnt(10)
	v_dot4c_i32_i8_e32 v74, v172, v16
	s_waitcnt vmcnt(9)
	v_dot4c_i32_i8_e32 v75, v176, v16
	s_waitcnt vmcnt(8)
	v_dot4c_i32_i8_e32 v76, v180, v16
	s_waitcnt vmcnt(7)
	v_dot4c_i32_i8_e32 v77, v184, v16
	s_waitcnt vmcnt(6)
	v_dot4c_i32_i8_e32 v78, v190, v16
	s_waitcnt vmcnt(5)
	v_dot4c_i32_i8_e32 v79, v194, v16
	s_waitcnt vmcnt(4)
	v_dot4c_i32_i8_e32 v80, v198, v16
	s_waitcnt vmcnt(3)
	v_dot4c_i32_i8_e32 v81, v202, v16
	s_waitcnt vmcnt(2)
	v_dot4c_i32_i8_e32 v82, v206, v16
	s_waitcnt vmcnt(1)
	v_dot4c_i32_i8_e32 v83, v210, v16
	v_dot4c_i32_i8_e32 v68, v149, v17
	v_dot4c_i32_i8_e32 v69, v153, v17
	v_dot4c_i32_i8_e32 v70, v157, v17
	v_dot4c_i32_i8_e32 v71, v161, v17
	v_dot4c_i32_i8_e32 v72, v165, v17
	v_dot4c_i32_i8_e32 v73, v169, v17
	v_dot4c_i32_i8_e32 v74, v173, v17
	v_dot4c_i32_i8_e32 v75, v177, v17
	v_dot4c_i32_i8_e32 v76, v181, v17
	v_dot4c_i32_i8_e32 v77, v185, v17
	v_dot4c_i32_i8_e32 v78, v191, v17
	v_dot4c_i32_i8_e32 v79, v195, v17
	v_dot4c_i32_i8_e32 v80, v199, v17
	v_dot4c_i32_i8_e32 v81, v203, v17
	v_dot4c_i32_i8_e32 v82, v207, v17
	v_dot4c_i32_i8_e32 v83, v211, v17
	v_dot4c_i32_i8_e32 v68, v150, v18
	v_dot4c_i32_i8_e32 v69, v154, v18
	v_dot4c_i32_i8_e32 v70, v158, v18
	v_dot4c_i32_i8_e32 v71, v162, v18
	v_dot4c_i32_i8_e32 v72, v166, v18
	v_dot4c_i32_i8_e32 v73, v170, v18
	v_dot4c_i32_i8_e32 v74, v174, v18
	v_dot4c_i32_i8_e32 v75, v178, v18
	v_dot4c_i32_i8_e32 v76, v182, v18
	v_dot4c_i32_i8_e32 v77, v186, v18
	v_dot4c_i32_i8_e32 v78, v192, v18
	v_dot4c_i32_i8_e32 v79, v196, v18
	v_dot4c_i32_i8_e32 v80, v200, v18
	v_dot4c_i32_i8_e32 v81, v204, v18
	v_dot4c_i32_i8_e32 v82, v208, v18
	v_dot4c_i32_i8_e32 v83, v212, v18
	v_dot4c_i32_i8_e32 v68, v151, v19
	v_dot4c_i32_i8_e32 v69, v155, v19
	v_dot4c_i32_i8_e32 v70, v159, v19
	v_dot4c_i32_i8_e32 v71, v163, v19
	v_dot4c_i32_i8_e32 v72, v167, v19
	v_dot4c_i32_i8_e32 v73, v171, v19
	v_dot4c_i32_i8_e32 v74, v175, v19
	v_dot4c_i32_i8_e32 v75, v179, v19
	v_dot4c_i32_i8_e32 v76, v183, v19
	v_dot4c_i32_i8_e32 v77, v187, v19
	v_dot4c_i32_i8_e32 v78, v193, v19
	v_dot4c_i32_i8_e32 v79, v197, v19
	v_dot4c_i32_i8_e32 v80, v201, v19
	v_dot4c_i32_i8_e32 v81, v205, v19
	v_dot4c_i32_i8_e32 v82, v209, v19
	v_dot4c_i32_i8_e32 v83, v213, v19
	v_add_u32_dpp v148, v68, v68 row_ror:8 row_mask:0xf bank_mask:0x3
	v_add_u32_dpp v148, v76, v76 row_ror:8 row_mask:0xf bank_mask:0xc
	v_add_u32_dpp v149, v69, v69 row_ror:8 row_mask:0xf bank_mask:0x3
	v_add_u32_dpp v149, v77, v77 row_ror:8 row_mask:0xf bank_mask:0xc
	v_add_u32_dpp v150, v70, v70 row_ror:8 row_mask:0xf bank_mask:0x3
	v_add_u32_dpp v150, v78, v78 row_ror:8 row_mask:0xf bank_mask:0xc
	v_add_u32_dpp v151, v71, v71 row_ror:8 row_mask:0xf bank_mask:0x3
; DI void wave_lds_sync() { asm volatile("s_waitcnt lgkmcnt(0)" ::: "memory"); __builtin_amdgcn_wave_barrier(); }
; DI void phase9(const Params& p, char* smem, int rep) {
;     ...
;       const int tok = __builtin_amdgcn_readfirstlane(c * 16 + w * 4 + t);
;       const int i0 = IDS[(size_t)tok * 128 + lane], i1 = IDS[(size_t)tok * 128 + 64 + lane];
;       const u32x4 hq = *(const u32x4*)(H2Q + (size_t)tok * D_ + s * 256 + l15 * 16);
;       wave_lds_sync();
;       lw[(lane & 3) * 32 + (lane >> 2)] = i0;
;       lw[(lane & 3) * 32 + 16 + (lane >> 2)] = i1;
;       wave_lds_sync();
;       const unsigned char* ub = U8 + s * 256 + l15 * 16;
; #pragma unroll
;       for (int batch = 0; batch < 2; ++batch) {
;         int ida[16];
; #pragma unroll
;         for (int q = 0; q < 4; ++q) { const int4 v = *(const int4*)(lw + g * 32 + batch * 16 + q * 4); ida[q * 4] = v.x; ida[q * 4 + 1] = v.y; ida[q * 4 + 2] = v.z; ida[q * 4 + 3] = v.w; }
;         u32x4 rows[16];
; #pragma unroll
;         for (int k = 0; k < 16; ++k) rows[k] = *(const u32x4*)(ub + (size_t)ida[k] * 2048);
;         int part[16];
; #pragma unroll
;         for (int k = 0; k < 16; ++k) {
;           int acc = 0;
; #pragma unroll
;           for (int d = 0; d < 4; ++d) acc = __builtin_amdgcn_sdot4((int)rows[k][d], (int)hq[d], acc, false);
;           part[k] = acc;
;         }
;         int q8[8], q4[4], q2[2];
; #pragma unroll
;         for (int k = 0; k < 8; ++k) q8[k] = (b3 ? part[8 + k] : part[k]) + __shfl_xor(b3 ? part[k] : part[8 + k], 8);
; #pragma unroll
;         for (int k = 0; k < 4; ++k) q4[k] = (b2 ? q8[4 + k] : q8[k]) + __shfl_xor(b2 ? q8[k] : q8[4 + k], 4);
; #pragma unroll
;         for (int k = 0; k < 2; ++k) q2[k] = (b1 ? q4[2 + k] : q4[k]) + __shfl_xor(b1 ? q4[k] : q4[2 + k], 2);
;         const int rr = (b0 ? q2[1] : q2[0]) + __shfl_xor(b0 ? q2[0] : q2[1], 1);
;         PA[((size_t)s * T_ + tok) * 128 + 4 * (batch * 16 + l15) + g] = rr;
	v_add_u32_dpp v151, v79, v79 row_ror:8 row_mask:0xf bank_mask:0xc
	v_add_u32_dpp v152, v72, v72 row_ror:8 row_mask:0xf bank_mask:0x3
	v_add_u32_dpp v152, v80, v80 row_ror:8 row_mask:0xf bank_mask:0xc
	v_add_u32_dpp v153, v73, v73 row_ror:8 row_mask:0xf bank_mask:0x3
	v_add_u32_dpp v153, v81, v81 row_ror:8 row_mask:0xf bank_mask:0xc
	v_add_u32_dpp v154, v74, v74 row_ror:8 row_mask:0xf bank_mask:0x3
	v_add_u32_dpp v154, v82, v82 row_ror:8 row_mask:0xf bank_mask:0xc
	v_add_u32_dpp v155, v75, v75 row_ror:8 row_mask:0xf bank_mask:0x3
	v_add_u32_dpp v155, v83, v83 row_ror:8 row_mask:0xf bank_mask:0xc
	v_add_u32_dpp v156, v148, v148 row_half_mirror row_mask:0xf bank_mask:0x5
	v_add_u32_dpp v156, v152, v152 row_half_mirror row_mask:0xf bank_mask:0xa
	v_add_u32_dpp v157, v149, v149 row_half_mirror row_mask:0xf bank_mask:0x5
	v_add_u32_dpp v157, v153, v153 row_half_mirror row_mask:0xf bank_mask:0xa
	v_add_u32_dpp v158, v150, v150 row_half_mirror row_mask:0xf bank_mask:0x5
	v_add_u32_dpp v158, v154, v154 row_half_mirror row_mask:0xf bank_mask:0xa
	v_add_u32_dpp v159, v151, v151 row_half_mirror row_mask:0xf bank_mask:0x5
	v_add_u32_dpp v159, v155, v155 row_half_mirror row_mask:0xf bank_mask:0xa
	v_add_u32_dpp v160, v156, v156 quad_perm:[2,3,0,1] row_mask:0xf bank_mask:0xf
	v_add_u32_dpp v161, v157, v157 quad_perm:[2,3,0,1] row_mask:0xf bank_mask:0xf
	v_add_u32_dpp v162, v158, v158 quad_perm:[2,3,0,1] row_mask:0xf bank_mask:0xf
	s_nop 0
	v_add_u32_dpp v163, v159, v159 quad_perm:[2,3,0,1] row_mask:0xf bank_mask:0xf
	v_cndmask_b32_e64 v164, v162, v160, s[2:3]
	v_cndmask_b32_e64 v165, v163, v161, s[2:3]
	s_nop 0
	s_nop 1
	v_add_u32_dpp v166, v164, v164 quad_perm:[1,0,3,2] row_mask:0xf bank_mask:0xf
	v_add_u32_dpp v167, v165, v165 quad_perm:[1,0,3,2] row_mask:0xf bank_mask:0xf
	v_cndmask_b32_e64 v168, v167, v166, s[4:5]
	global_store_dword v214, v168, s[14:15] offset:256
	s_add_i32 s36, s34, 2
	s_lshl_b32 s46, s36, 9
	s_add_i32 s46, s46, s24
	s_add_i32 s37, s34, 3
	s_lshl_b32 s47, s37, 9
	s_add_u32 s42, s6, s47
	s_addc_u32 s43, s7, 0
	s_lshl_b32 s47, s37, 11
	s_add_u32 s44, s22, s47
	s_addc_u32 s45, s23, 0
	global_load_dword v10, v3, s[42:43]
	global_load_dword v11, v3, s[42:43] offset:256
	global_load_dwordx4 v[16:19], v2, s[44:45]
	s_waitcnt lgkmcnt(0)
	v_lshl_add_u32 v20, v20, 11, v2
	v_lshl_add_u32 v21, v21, 11, v2
	v_lshl_add_u32 v22, v22, 11, v2
	v_lshl_add_u32 v23, v23, 11, v2
	v_lshl_add_u32 v24, v24, 11, v2
	v_lshl_add_u32 v25, v25, 11, v2
	v_lshl_add_u32 v26, v26, 11, v2
	v_lshl_add_u32 v27, v27, 11, v2
	v_lshl_add_u32 v28, v28, 11, v2
	v_lshl_add_u32 v29, v29, 11, v2
	v_lshl_add_u32 v30, v30, 11, v2
	v_lshl_add_u32 v31, v31, 11, v2
	v_lshl_add_u32 v32, v32, 11, v2
	v_lshl_add_u32 v33, v33, 11, v2
	v_lshl_add_u32 v34, v34, 11, v2
	v_lshl_add_u32 v35, v35, 11, v2
	v_lshl_add_u32 v36, v36, 11, v2
	v_lshl_add_u32 v37, v37, 11, v2
	v_lshl_add_u32 v38, v38, 11, v2
	v_lshl_add_u32 v39, v39, 11, v2
	v_lshl_add_u32 v40, v40, 11, v2
	v_lshl_add_u32 v41, v41, 11, v2
	v_lshl_add_u32 v42, v42, 11, v2
	v_lshl_add_u32 v43, v43, 11, v2
	v_lshl_add_u32 v44, v44, 11, v2
	v_lshl_add_u32 v45, v45, 11, v2
	v_lshl_add_u32 v46, v46, 11, v2
	v_lshl_add_u32 v47, v47, 11, v2
	v_lshl_add_u32 v48, v48, 11, v2
	v_lshl_add_u32 v49, v49, 11, v2
	v_lshl_add_u32 v50, v50, 11, v2
	v_lshl_add_u32 v51, v51, 11, v2
	global_load_dwordx4 v[84:87], v20, s[20:21]
	global_load_dwordx4 v[88:91], v21, s[20:21]
	global_load_dwordx4 v[92:95], v22, s[20:21]
	global_load_dwordx4 v[96:99], v23, s[20:21]
	global_load_dwordx4 v[100:103], v24, s[20:21]
	global_load_dwordx4 v[104:107], v25, s[20:21]
	global_load_dwordx4 v[108:111], v26, s[20:21]
	global_load_dwordx4 v[112:115], v27, s[20:21]
	global_load_dwordx4 v[116:119], v28, s[20:21]
	global_load_dwordx4 v[120:123], v29, s[20:21]
	global_load_dwordx4 v[124:127], v30, s[20:21]
	global_load_dwordx4 v[128:131], v31, s[20:21]
	global_load_dwordx4 v[132:135], v32, s[20:21]
	global_load_dwordx4 v[136:139], v33, s[20:21]
	global_load_dwordx4 v[140:143], v34, s[20:21]
	global_load_dwordx4 v[144:147], v35, s[20:21]
	global_load_dwordx4 v[148:151], v36, s[20:21]
	global_load_dwordx4 v[152:155], v37, s[20:21]
	global_load_dwordx4 v[156:159], v38, s[20:21]
	global_load_dwordx4 v[160:163], v39, s[20:21]
	global_load_dwordx4 v[164:167], v40, s[20:21]
	global_load_dwordx4 v[168:171], v41, s[20:21]
	global_load_dwordx4 v[172:175], v42, s[20:21]
	global_load_dwordx4 v[176:179], v43, s[20:21]
	global_load_dwordx4 v[180:183], v44, s[20:21]
	global_load_dwordx4 v[184:187], v45, s[20:21]
	global_load_dwordx4 v[190:193], v46, s[20:21]
	global_load_dwordx4 v[194:197], v47, s[20:21]
	global_load_dwordx4 v[198:201], v48, s[20:21]
	global_load_dwordx4 v[202:205], v49, s[20:21]
	global_load_dwordx4 v[206:209], v50, s[20:21]
	global_load_dwordx4 v[210:213], v51, s[20:21]
	v_mov_b32_e32 v52, 0
	v_mov_b32_e32 v53, 0
	v_mov_b32_e32 v54, 0
	v_mov_b32_e32 v55, 0
	v_mov_b32_e32 v56, 0
	v_mov_b32_e32 v57, 0
	v_mov_b32_e32 v58, 0
	v_mov_b32_e32 v59, 0
	v_mov_b32_e32 v60, 0
	v_mov_b32_e32 v61, 0
	v_mov_b32_e32 v62, 0
	v_mov_b32_e32 v63, 0
	v_mov_b32_e32 v64, 0
	v_mov_b32_e32 v65, 0
	v_mov_b32_e32 v66, 0
	v_mov_b32_e32 v67, 0
	v_mov_b32_e32 v68, 0
	v_mov_b32_e32 v69, 0
	v_mov_b32_e32 v70, 0
	v_mov_b32_e32 v71, 0
	v_mov_b32_e32 v72, 0
	v_mov_b32_e32 v73, 0
	v_mov_b32_e32 v74, 0
	v_mov_b32_e32 v75, 0
	v_mov_b32_e32 v76, 0
	v_mov_b32_e32 v77, 0
	v_mov_b32_e32 v78, 0
	v_mov_b32_e32 v79, 0
	v_mov_b32_e32 v80, 0
	v_mov_b32_e32 v81, 0
	v_mov_b32_e32 v82, 0
	v_mov_b32_e32 v83, 0
	s_waitcnt vmcnt(31)
	v_dot4c_i32_i8_e32 v52, v84, v12
	s_waitcnt vmcnt(30)
	v_dot4c_i32_i8_e32 v53, v88, v12
	s_waitcnt vmcnt(29)
; DI void wave_lds_sync() { asm volatile("s_waitcnt lgkmcnt(0)" ::: "memory"); __builtin_amdgcn_wave_barrier(); }
; DI void phase9(const Params& p, char* smem, int rep) {
;     ...
;       const int tok = __builtin_amdgcn_readfirstlane(c * 16 + w * 4 + t);
;       const int i0 = IDS[(size_t)tok * 128 + lane], i1 = IDS[(size_t)tok * 128 + 64 + lane];
;       const u32x4 hq = *(const u32x4*)(H2Q + (size_t)tok * D_ + s * 256 + l15 * 16);
;       wave_lds_sync();
;       lw[(lane & 3) * 32 + (lane >> 2)] = i0;
;       lw[(lane & 3) * 32 + 16 + (lane >> 2)] = i1;
;       wave_lds_sync();
;       const unsigned char* ub = U8 + s * 256 + l15 * 16;
; #pragma unroll
;       for (int batch = 0; batch < 2; ++batch) {
;         int ida[16];
; #pragma unroll
;         for (int q = 0; q < 4; ++q) { const int4 v = *(const int4*)(lw + g * 32 + batch * 16 + q * 4); ida[q * 4] = v.x; ida[q * 4 + 1] = v.y; ida[q * 4 + 2] = v.z; ida[q * 4 + 3] = v.w; }
;         u32x4 rows[16];
; #pragma unroll
;         for (int k = 0; k < 16; ++k) rows[k] = *(const u32x4*)(ub + (size_t)ida[k] * 2048);
;         int part[16];
; #pragma unroll
;         for (int k = 0; k < 16; ++k) {
;           int acc = 0;
; #pragma unroll
;           for (int d = 0; d < 4; ++d) acc = __builtin_amdgcn_sdot4((int)rows[k][d], (int)hq[d], acc, false);
;           part[k] = acc;
;         }
;         int q8[8], q4[4], q2[2];
; #pragma unroll
;         for (int k = 0; k < 8; ++k) q8[k] = (b3 ? part[8 + k] : part[k]) + __shfl_xor(b3 ? part[k] : part[8 + k], 8);
; #pragma unroll
;         for (int k = 0; k < 4; ++k) q4[k] = (b2 ? q8[4 + k] : q8[k]) + __shfl_xor(b2 ? q8[k] : q8[4 + k], 4);
; #pragma unroll
;         for (int k = 0; k < 2; ++k) q2[k] = (b1 ? q4[2 + k] : q4[k]) + __shfl_xor(b1 ? q4[k] : q4[2 + k], 2);
;         const int rr = (b0 ? q2[1] : q2[0]) + __shfl_xor(b0 ? q2[0] : q2[1], 1);
;         PA[((size_t)s * T_ + tok) * 128 + 4 * (batch * 16 + l15) + g] = rr;
	v_dot4c_i32_i8_e32 v54, v92, v12
	s_waitcnt vmcnt(28)
	v_dot4c_i32_i8_e32 v55, v96, v12
	s_waitcnt vmcnt(27)
	v_dot4c_i32_i8_e32 v56, v100, v12
	s_waitcnt vmcnt(26)
	v_dot4c_i32_i8_e32 v57, v104, v12
	s_waitcnt vmcnt(25)
	v_dot4c_i32_i8_e32 v58, v108, v12
	s_waitcnt vmcnt(24)
	v_dot4c_i32_i8_e32 v59, v112, v12
	s_waitcnt vmcnt(23)
	v_dot4c_i32_i8_e32 v60, v116, v12
	s_waitcnt vmcnt(22)
	v_dot4c_i32_i8_e32 v61, v120, v12
	s_waitcnt vmcnt(21)
	v_dot4c_i32_i8_e32 v62, v124, v12
	s_waitcnt vmcnt(20)
	v_dot4c_i32_i8_e32 v63, v128, v12
	s_waitcnt vmcnt(19)
	v_dot4c_i32_i8_e32 v64, v132, v12
	s_waitcnt vmcnt(18)
	v_dot4c_i32_i8_e32 v65, v136, v12
	s_waitcnt vmcnt(17)
	v_dot4c_i32_i8_e32 v66, v140, v12
	s_waitcnt vmcnt(16)
	v_dot4c_i32_i8_e32 v67, v144, v12
	v_dot4c_i32_i8_e32 v52, v85, v13
	v_dot4c_i32_i8_e32 v53, v89, v13
	v_dot4c_i32_i8_e32 v54, v93, v13
	v_dot4c_i32_i8_e32 v55, v97, v13
	v_dot4c_i32_i8_e32 v56, v101, v13
	v_dot4c_i32_i8_e32 v57, v105, v13
	v_dot4c_i32_i8_e32 v58, v109, v13
	v_dot4c_i32_i8_e32 v59, v113, v13
	v_dot4c_i32_i8_e32 v60, v117, v13
	v_dot4c_i32_i8_e32 v61, v121, v13
	v_dot4c_i32_i8_e32 v62, v125, v13
	v_dot4c_i32_i8_e32 v63, v129, v13
	v_dot4c_i32_i8_e32 v64, v133, v13
	v_dot4c_i32_i8_e32 v65, v137, v13
	v_dot4c_i32_i8_e32 v66, v141, v13
	v_dot4c_i32_i8_e32 v67, v145, v13
	v_dot4c_i32_i8_e32 v52, v86, v14
	v_dot4c_i32_i8_e32 v53, v90, v14
	v_dot4c_i32_i8_e32 v54, v94, v14
	v_dot4c_i32_i8_e32 v55, v98, v14
	v_dot4c_i32_i8_e32 v56, v102, v14
	v_dot4c_i32_i8_e32 v57, v106, v14
	v_dot4c_i32_i8_e32 v58, v110, v14
	v_dot4c_i32_i8_e32 v59, v114, v14
	v_dot4c_i32_i8_e32 v60, v118, v14
	v_dot4c_i32_i8_e32 v61, v122, v14
	v_dot4c_i32_i8_e32 v62, v126, v14
	v_dot4c_i32_i8_e32 v63, v130, v14
	v_dot4c_i32_i8_e32 v64, v134, v14
	v_dot4c_i32_i8_e32 v65, v138, v14
	v_dot4c_i32_i8_e32 v66, v142, v14
	v_dot4c_i32_i8_e32 v67, v146, v14
	v_dot4c_i32_i8_e32 v52, v87, v15
	v_dot4c_i32_i8_e32 v53, v91, v15
	v_dot4c_i32_i8_e32 v54, v95, v15
	v_dot4c_i32_i8_e32 v55, v99, v15
	v_dot4c_i32_i8_e32 v56, v103, v15
	v_dot4c_i32_i8_e32 v57, v107, v15
	v_dot4c_i32_i8_e32 v58, v111, v15
	v_dot4c_i32_i8_e32 v59, v115, v15
	v_dot4c_i32_i8_e32 v60, v119, v15
	v_dot4c_i32_i8_e32 v61, v123, v15
	v_dot4c_i32_i8_e32 v62, v127, v15
	v_dot4c_i32_i8_e32 v63, v131, v15
	v_dot4c_i32_i8_e32 v64, v135, v15
	v_dot4c_i32_i8_e32 v65, v139, v15
	v_dot4c_i32_i8_e32 v66, v143, v15
	v_dot4c_i32_i8_e32 v67, v147, v15
	ds_write2_b32 v5, v10, v11 offset0:4 offset1:20
	s_waitcnt lgkmcnt(0)
	ds_read_b128 v[20:23], v6 offset:16
	ds_read_b128 v[24:27], v6 offset:32
	ds_read_b128 v[28:31], v6 offset:48
	ds_read_b128 v[32:35], v6 offset:64
	ds_read_b128 v[36:39], v6 offset:80
	ds_read_b128 v[40:43], v6 offset:96
	ds_read_b128 v[44:47], v6 offset:112
	ds_read_b128 v[48:51], v6 offset:128
	v_add_u32_dpp v84, v52, v52 row_ror:8 row_mask:0xf bank_mask:0x3
	v_add_u32_dpp v84, v60, v60 row_ror:8 row_mask:0xf bank_mask:0xc
	v_add_u32_dpp v85, v53, v53 row_ror:8 row_mask:0xf bank_mask:0x3
	v_add_u32_dpp v85, v61, v61 row_ror:8 row_mask:0xf bank_mask:0xc
	v_add_u32_dpp v86, v54, v54 row_ror:8 row_mask:0xf bank_mask:0x3
	v_add_u32_dpp v86, v62, v62 row_ror:8 row_mask:0xf bank_mask:0xc
	v_add_u32_dpp v87, v55, v55 row_ror:8 row_mask:0xf bank_mask:0x3
	v_add_u32_dpp v87, v63, v63 row_ror:8 row_mask:0xf bank_mask:0xc
	v_add_u32_dpp v88, v56, v56 row_ror:8 row_mask:0xf bank_mask:0x3
	v_add_u32_dpp v88, v64, v64 row_ror:8 row_mask:0xf bank_mask:0xc
	v_add_u32_dpp v89, v57, v57 row_ror:8 row_mask:0xf bank_mask:0x3
	v_add_u32_dpp v89, v65, v65 row_ror:8 row_mask:0xf bank_mask:0xc
	v_add_u32_dpp v90, v58, v58 row_ror:8 row_mask:0xf bank_mask:0x3
	v_add_u32_dpp v90, v66, v66 row_ror:8 row_mask:0xf bank_mask:0xc
	v_add_u32_dpp v91, v59, v59 row_ror:8 row_mask:0xf bank_mask:0x3
	v_add_u32_dpp v91, v67, v67 row_ror:8 row_mask:0xf bank_mask:0xc
	v_add_u32_dpp v92, v84, v84 row_half_mirror row_mask:0xf bank_mask:0x5
	v_add_u32_dpp v92, v88, v88 row_half_mirror row_mask:0xf bank_mask:0xa
	v_add_u32_dpp v93, v85, v85 row_half_mirror row_mask:0xf bank_mask:0x5
	v_add_u32_dpp v93, v89, v89 row_half_mirror row_mask:0xf bank_mask:0xa
	v_add_u32_dpp v94, v86, v86 row_half_mirror row_mask:0xf bank_mask:0x5
	v_add_u32_dpp v94, v90, v90 row_half_mirror row_mask:0xf bank_mask:0xa
	v_add_u32_dpp v95, v87, v87 row_half_mirror row_mask:0xf bank_mask:0x5
	v_add_u32_dpp v95, v91, v91 row_half_mirror row_mask:0xf bank_mask:0xa
	v_add_u32_dpp v96, v92, v92 quad_perm:[2,3,0,1] row_mask:0xf bank_mask:0xf
	v_add_u32_dpp v97, v93, v93 quad_perm:[2,3,0,1] row_mask:0xf bank_mask:0xf
	v_add_u32_dpp v98, v94, v94 quad_perm:[2,3,0,1] row_mask:0xf bank_mask:0xf
	s_nop 0
	v_add_u32_dpp v99, v95, v95 quad_perm:[2,3,0,1] row_mask:0xf bank_mask:0xf
	v_cndmask_b32_e64 v100, v98, v96, s[2:3]
	v_cndmask_b32_e64 v101, v99, v97, s[2:3]
	v_add_u32_e32 v214, s46, v4
	s_nop 1
	v_add_u32_dpp v102, v100, v100 quad_perm:[1,0,3,2] row_mask:0xf bank_mask:0xf
	v_add_u32_dpp v103, v101, v101 quad_perm:[1,0,3,2] row_mask:0xf bank_mask:0xf
	v_cndmask_b32_e64 v104, v103, v102, s[4:5]
	global_store_dword v214, v104, s[14:15]
	s_waitcnt vmcnt(16)
	v_dot4c_i32_i8_e32 v68, v148, v12
	s_waitcnt vmcnt(15)
	v_dot4c_i32_i8_e32 v69, v152, v12
	s_waitcnt vmcnt(14)
	v_dot4c_i32_i8_e32 v70, v156, v12
	s_waitcnt vmcnt(13)
	v_dot4c_i32_i8_e32 v71, v160, v12
	s_waitcnt vmcnt(12)
	v_dot4c_i32_i8_e32 v72, v164, v12
	s_waitcnt vmcnt(11)
	v_dot4c_i32_i8_e32 v73, v168, v12
	s_waitcnt vmcnt(10)
	v_dot4c_i32_i8_e32 v74, v172, v12
	s_waitcnt vmcnt(9)
	v_dot4c_i32_i8_e32 v75, v176, v12
	s_waitcnt vmcnt(8)
	v_dot4c_i32_i8_e32 v76, v180, v12
	s_waitcnt vmcnt(7)
; DI void wave_lds_sync() { asm volatile("s_waitcnt lgkmcnt(0)" ::: "memory"); __builtin_amdgcn_wave_barrier(); }
; DI void phase9(const Params& p, char* smem, int rep) {
;     ...
;       const int tok = __builtin_amdgcn_readfirstlane(c * 16 + w * 4 + t);
;       const int i0 = IDS[(size_t)tok * 128 + lane], i1 = IDS[(size_t)tok * 128 + 64 + lane];
;       const u32x4 hq = *(const u32x4*)(H2Q + (size_t)tok * D_ + s * 256 + l15 * 16);
;       wave_lds_sync();
;       lw[(lane & 3) * 32 + (lane >> 2)] = i0;
;       lw[(lane & 3) * 32 + 16 + (lane >> 2)] = i1;
;       wave_lds_sync();
;       const unsigned char* ub = U8 + s * 256 + l15 * 16;
; #pragma unroll
;       for (int batch = 0; batch < 2; ++batch) {
;         int ida[16];
; #pragma unroll
;         for (int q = 0; q < 4; ++q) { const int4 v = *(const int4*)(lw + g * 32 + batch * 16 + q * 4); ida[q * 4] = v.x; ida[q * 4 + 1] = v.y; ida[q * 4 + 2] = v.z; ida[q * 4 + 3] = v.w; }
;         u32x4 rows[16];
; #pragma unroll
;         for (int k = 0; k < 16; ++k) rows[k] = *(const u32x4*)(ub + (size_t)ida[k] * 2048);
;         int part[16];
; #pragma unroll
;         for (int k = 0; k < 16; ++k) {
;           int acc = 0;
; #pragma unroll
;           for (int d = 0; d < 4; ++d) acc = __builtin_amdgcn_sdot4((int)rows[k][d], (int)hq[d], acc, false);
;           part[k] = acc;
;         }
;         int q8[8], q4[4], q2[2];
; #pragma unroll
;         for (int k = 0; k < 8; ++k) q8[k] = (b3 ? part[8 + k] : part[k]) + __shfl_xor(b3 ? part[k] : part[8 + k], 8);
; #pragma unroll
;         for (int k = 0; k < 4; ++k) q4[k] = (b2 ? q8[4 + k] : q8[k]) + __shfl_xor(b2 ? q8[k] : q8[4 + k], 4);
; #pragma unroll
;         for (int k = 0; k < 2; ++k) q2[k] = (b1 ? q4[2 + k] : q4[k]) + __shfl_xor(b1 ? q4[k] : q4[2 + k], 2);
;         const int rr = (b0 ? q2[1] : q2[0]) + __shfl_xor(b0 ? q2[0] : q2[1], 1);
;         PA[((size_t)s * T_ + tok) * 128 + 4 * (batch * 16 + l15) + g] = rr;
	v_dot4c_i32_i8_e32 v77, v184, v12
	s_waitcnt vmcnt(6)
	v_dot4c_i32_i8_e32 v78, v190, v12
	s_waitcnt vmcnt(5)
	v_dot4c_i32_i8_e32 v79, v194, v12
	s_waitcnt vmcnt(4)
	v_dot4c_i32_i8_e32 v80, v198, v12
	s_waitcnt vmcnt(3)
	v_dot4c_i32_i8_e32 v81, v202, v12
	s_waitcnt vmcnt(2)
	v_dot4c_i32_i8_e32 v82, v206, v12
	s_waitcnt vmcnt(1)
	v_dot4c_i32_i8_e32 v83, v210, v12
	v_dot4c_i32_i8_e32 v68, v149, v13
	v_dot4c_i32_i8_e32 v69, v153, v13
	v_dot4c_i32_i8_e32 v70, v157, v13
	v_dot4c_i32_i8_e32 v71, v161, v13
	v_dot4c_i32_i8_e32 v72, v165, v13
	v_dot4c_i32_i8_e32 v73, v169, v13
	v_dot4c_i32_i8_e32 v74, v173, v13
	v_dot4c_i32_i8_e32 v75, v177, v13
	v_dot4c_i32_i8_e32 v76, v181, v13
	v_dot4c_i32_i8_e32 v77, v185, v13
	v_dot4c_i32_i8_e32 v78, v191, v13
	v_dot4c_i32_i8_e32 v79, v195, v13
	v_dot4c_i32_i8_e32 v80, v199, v13
	v_dot4c_i32_i8_e32 v81, v203, v13
	v_dot4c_i32_i8_e32 v82, v207, v13
	v_dot4c_i32_i8_e32 v83, v211, v13
	v_dot4c_i32_i8_e32 v68, v150, v14
	v_dot4c_i32_i8_e32 v69, v154, v14
	v_dot4c_i32_i8_e32 v70, v158, v14
	v_dot4c_i32_i8_e32 v71, v162, v14
	v_dot4c_i32_i8_e32 v72, v166, v14
	v_dot4c_i32_i8_e32 v73, v170, v14
	v_dot4c_i32_i8_e32 v74, v174, v14
	v_dot4c_i32_i8_e32 v75, v178, v14
	v_dot4c_i32_i8_e32 v76, v182, v14
	v_dot4c_i32_i8_e32 v77, v186, v14
	v_dot4c_i32_i8_e32 v78, v192, v14
	v_dot4c_i32_i8_e32 v79, v196, v14
	v_dot4c_i32_i8_e32 v80, v200, v14
	v_dot4c_i32_i8_e32 v81, v204, v14
	v_dot4c_i32_i8_e32 v82, v208, v14
	v_dot4c_i32_i8_e32 v83, v212, v14
	v_dot4c_i32_i8_e32 v68, v151, v15
	v_dot4c_i32_i8_e32 v69, v155, v15
	v_dot4c_i32_i8_e32 v70, v159, v15
	v_dot4c_i32_i8_e32 v71, v163, v15
	v_dot4c_i32_i8_e32 v72, v167, v15
	v_dot4c_i32_i8_e32 v73, v171, v15
	v_dot4c_i32_i8_e32 v74, v175, v15
	v_dot4c_i32_i8_e32 v75, v179, v15
	v_dot4c_i32_i8_e32 v76, v183, v15
	v_dot4c_i32_i8_e32 v77, v187, v15
	v_dot4c_i32_i8_e32 v78, v193, v15
	v_dot4c_i32_i8_e32 v79, v197, v15
	v_dot4c_i32_i8_e32 v80, v201, v15
	v_dot4c_i32_i8_e32 v81, v205, v15
	v_dot4c_i32_i8_e32 v82, v209, v15
	v_dot4c_i32_i8_e32 v83, v213, v15
	v_add_u32_dpp v148, v68, v68 row_ror:8 row_mask:0xf bank_mask:0x3
	v_add_u32_dpp v148, v76, v76 row_ror:8 row_mask:0xf bank_mask:0xc
	v_add_u32_dpp v149, v69, v69 row_ror:8 row_mask:0xf bank_mask:0x3
	v_add_u32_dpp v149, v77, v77 row_ror:8 row_mask:0xf bank_mask:0xc
	v_add_u32_dpp v150, v70, v70 row_ror:8 row_mask:0xf bank_mask:0x3
	v_add_u32_dpp v150, v78, v78 row_ror:8 row_mask:0xf bank_mask:0xc
	v_add_u32_dpp v151, v71, v71 row_ror:8 row_mask:0xf bank_mask:0x3
	v_add_u32_dpp v151, v79, v79 row_ror:8 row_mask:0xf bank_mask:0xc
	v_add_u32_dpp v152, v72, v72 row_ror:8 row_mask:0xf bank_mask:0x3
	v_add_u32_dpp v152, v80, v80 row_ror:8 row_mask:0xf bank_mask:0xc
	v_add_u32_dpp v153, v73, v73 row_ror:8 row_mask:0xf bank_mask:0x3
	v_add_u32_dpp v153, v81, v81 row_ror:8 row_mask:0xf bank_mask:0xc
	v_add_u32_dpp v154, v74, v74 row_ror:8 row_mask:0xf bank_mask:0x3
	v_add_u32_dpp v154, v82, v82 row_ror:8 row_mask:0xf bank_mask:0xc
	v_add_u32_dpp v155, v75, v75 row_ror:8 row_mask:0xf bank_mask:0x3
	v_add_u32_dpp v155, v83, v83 row_ror:8 row_mask:0xf bank_mask:0xc
	v_add_u32_dpp v156, v148, v148 row_half_mirror row_mask:0xf bank_mask:0x5
	v_add_u32_dpp v156, v152, v152 row_half_mirror row_mask:0xf bank_mask:0xa
	v_add_u32_dpp v157, v149, v149 row_half_mirror row_mask:0xf bank_mask:0x5
	v_add_u32_dpp v157, v153, v153 row_half_mirror row_mask:0xf bank_mask:0xa
	v_add_u32_dpp v158, v150, v150 row_half_mirror row_mask:0xf bank_mask:0x5
	v_add_u32_dpp v158, v154, v154 row_half_mirror row_mask:0xf bank_mask:0xa
	v_add_u32_dpp v159, v151, v151 row_half_mirror row_mask:0xf bank_mask:0x5
	v_add_u32_dpp v159, v155, v155 row_half_mirror row_mask:0xf bank_mask:0xa
	v_add_u32_dpp v160, v156, v156 quad_perm:[2,3,0,1] row_mask:0xf bank_mask:0xf
	v_add_u32_dpp v161, v157, v157 quad_perm:[2,3,0,1] row_mask:0xf bank_mask:0xf
	v_add_u32_dpp v162, v158, v158 quad_perm:[2,3,0,1] row_mask:0xf bank_mask:0xf
	s_nop 0
	v_add_u32_dpp v163, v159, v159 quad_perm:[2,3,0,1] row_mask:0xf bank_mask:0xf
	v_cndmask_b32_e64 v164, v162, v160, s[2:3]
	v_cndmask_b32_e64 v165, v163, v161, s[2:3]
	s_nop 0
	s_nop 1
	v_add_u32_dpp v166, v164, v164 quad_perm:[1,0,3,2] row_mask:0xf bank_mask:0xf
	v_add_u32_dpp v167, v165, v165 quad_perm:[1,0,3,2] row_mask:0xf bank_mask:0xf
	v_cndmask_b32_e64 v168, v167, v166, s[4:5]
	global_store_dword v214, v168, s[14:15] offset:256
	s_add_i32 s36, s34, 3
	s_lshl_b32 s46, s36, 9
	s_add_i32 s46, s46, s24
	s_add_i32 s37, s34, 4
	s_add_i32 s51, s48, 1
	s_cmp_lt_u32 s51, s49
	s_cselect_b32 s37, s37, 8192
	s_cmp_lt_u32 s37, 8192
	s_cselect_b32 s37, s37, 0
	s_lshl_b32 s47, s37, 9
	s_add_u32 s42, s6, s47
	s_addc_u32 s43, s7, 0
	s_lshl_b32 s47, s37, 11
	s_add_u32 s44, s22, s47
	s_addc_u32 s45, s23, 0
	global_load_dword v10, v3, s[42:43]
	global_load_dword v11, v3, s[42:43] offset:256
	global_load_dwordx4 v[12:15], v2, s[44:45]
	s_waitcnt lgkmcnt(0)
; DI void wave_lds_sync() { asm volatile("s_waitcnt lgkmcnt(0)" ::: "memory"); __builtin_amdgcn_wave_barrier(); }
; DI void phase9(const Params& p, char* smem, int rep) {
;     ...
;       const int tok = __builtin_amdgcn_readfirstlane(c * 16 + w * 4 + t);
;       const int i0 = IDS[(size_t)tok * 128 + lane], i1 = IDS[(size_t)tok * 128 + 64 + lane];
;       const u32x4 hq = *(const u32x4*)(H2Q + (size_t)tok * D_ + s * 256 + l15 * 16);
;       wave_lds_sync();
;       lw[(lane & 3) * 32 + (lane >> 2)] = i0;
;       lw[(lane & 3) * 32 + 16 + (lane >> 2)] = i1;
;       wave_lds_sync();
;       const unsigned char* ub = U8 + s * 256 + l15 * 16;
; #pragma unroll
;       for (int batch = 0; batch < 2; ++batch) {
;         int ida[16];
; #pragma unroll
;         for (int q = 0; q < 4; ++q) { const int4 v = *(const int4*)(lw + g * 32 + batch * 16 + q * 4); ida[q * 4] = v.x; ida[q * 4 + 1] = v.y; ida[q * 4 + 2] = v.z; ida[q * 4 + 3] = v.w; }
;         u32x4 rows[16];
; #pragma unroll
;         for (int k = 0; k < 16; ++k) rows[k] = *(const u32x4*)(ub + (size_t)ida[k] * 2048);
;         int part[16];
; #pragma unroll
;         for (int k = 0; k < 16; ++k) {
;           int acc = 0;
; #pragma unroll
;           for (int d = 0; d < 4; ++d) acc = __builtin_amdgcn_sdot4((int)rows[k][d], (int)hq[d], acc, false);
;           part[k] = acc;
;         }
;         int q8[8], q4[4], q2[2];
; #pragma unroll
;         for (int k = 0; k < 8; ++k) q8[k] = (b3 ? part[8 + k] : part[k]) + __shfl_xor(b3 ? part[k] : part[8 + k], 8);
; #pragma unroll
;         for (int k = 0; k < 4; ++k) q4[k] = (b2 ? q8[4 + k] : q8[k]) + __shfl_xor(b2 ? q8[k] : q8[4 + k], 4);
; #pragma unroll
;         for (int k = 0; k < 2; ++k) q2[k] = (b1 ? q4[2 + k] : q4[k]) + __shfl_xor(b1 ? q4[k] : q4[2 + k], 2);
;         const int rr = (b0 ? q2[1] : q2[0]) + __shfl_xor(b0 ? q2[0] : q2[1], 1);
;         PA[((size_t)s * T_ + tok) * 128 + 4 * (batch * 16 + l15) + g] = rr;
	v_lshl_add_u32 v20, v20, 11, v2
	v_lshl_add_u32 v21, v21, 11, v2
	v_lshl_add_u32 v22, v22, 11, v2
	v_lshl_add_u32 v23, v23, 11, v2
	v_lshl_add_u32 v24, v24, 11, v2
	v_lshl_add_u32 v25, v25, 11, v2
	v_lshl_add_u32 v26, v26, 11, v2
	v_lshl_add_u32 v27, v27, 11, v2
	v_lshl_add_u32 v28, v28, 11, v2
	v_lshl_add_u32 v29, v29, 11, v2
	v_lshl_add_u32 v30, v30, 11, v2
	v_lshl_add_u32 v31, v31, 11, v2
	v_lshl_add_u32 v32, v32, 11, v2
	v_lshl_add_u32 v33, v33, 11, v2
	v_lshl_add_u32 v34, v34, 11, v2
	v_lshl_add_u32 v35, v35, 11, v2
	v_lshl_add_u32 v36, v36, 11, v2
	v_lshl_add_u32 v37, v37, 11, v2
	v_lshl_add_u32 v38, v38, 11, v2
	v_lshl_add_u32 v39, v39, 11, v2
	v_lshl_add_u32 v40, v40, 11, v2
	v_lshl_add_u32 v41, v41, 11, v2
	v_lshl_add_u32 v42, v42, 11, v2
	v_lshl_add_u32 v43, v43, 11, v2
	v_lshl_add_u32 v44, v44, 11, v2
	v_lshl_add_u32 v45, v45, 11, v2
	v_lshl_add_u32 v46, v46, 11, v2
	v_lshl_add_u32 v47, v47, 11, v2
	v_lshl_add_u32 v48, v48, 11, v2
	v_lshl_add_u32 v49, v49, 11, v2
	v_lshl_add_u32 v50, v50, 11, v2
	v_lshl_add_u32 v51, v51, 11, v2
	global_load_dwordx4 v[84:87], v20, s[20:21]
	global_load_dwordx4 v[88:91], v21, s[20:21]
	global_load_dwordx4 v[92:95], v22, s[20:21]
	global_load_dwordx4 v[96:99], v23, s[20:21]
	global_load_dwordx4 v[100:103], v24, s[20:21]
	global_load_dwordx4 v[104:107], v25, s[20:21]
	global_load_dwordx4 v[108:111], v26, s[20:21]
	global_load_dwordx4 v[112:115], v27, s[20:21]
	global_load_dwordx4 v[116:119], v28, s[20:21]
	global_load_dwordx4 v[120:123], v29, s[20:21]
	global_load_dwordx4 v[124:127], v30, s[20:21]
	global_load_dwordx4 v[128:131], v31, s[20:21]
	global_load_dwordx4 v[132:135], v32, s[20:21]
	global_load_dwordx4 v[136:139], v33, s[20:21]
	global_load_dwordx4 v[140:143], v34, s[20:21]
	global_load_dwordx4 v[144:147], v35, s[20:21]
	global_load_dwordx4 v[148:151], v36, s[20:21]
	global_load_dwordx4 v[152:155], v37, s[20:21]
	global_load_dwordx4 v[156:159], v38, s[20:21]
	global_load_dwordx4 v[160:163], v39, s[20:21]
	global_load_dwordx4 v[164:167], v40, s[20:21]
	global_load_dwordx4 v[168:171], v41, s[20:21]
	global_load_dwordx4 v[172:175], v42, s[20:21]
	global_load_dwordx4 v[176:179], v43, s[20:21]
	global_load_dwordx4 v[180:183], v44, s[20:21]
	global_load_dwordx4 v[184:187], v45, s[20:21]
	global_load_dwordx4 v[190:193], v46, s[20:21]
	global_load_dwordx4 v[194:197], v47, s[20:21]
	global_load_dwordx4 v[198:201], v48, s[20:21]
	global_load_dwordx4 v[202:205], v49, s[20:21]
	global_load_dwordx4 v[206:209], v50, s[20:21]
	global_load_dwordx4 v[210:213], v51, s[20:21]
	v_mov_b32_e32 v52, 0
	v_mov_b32_e32 v53, 0
	v_mov_b32_e32 v54, 0
	v_mov_b32_e32 v55, 0
	v_mov_b32_e32 v56, 0
	v_mov_b32_e32 v57, 0
	v_mov_b32_e32 v58, 0
	v_mov_b32_e32 v59, 0
	v_mov_b32_e32 v60, 0
	v_mov_b32_e32 v61, 0
	v_mov_b32_e32 v62, 0
	v_mov_b32_e32 v63, 0
	v_mov_b32_e32 v64, 0
	v_mov_b32_e32 v65, 0
	v_mov_b32_e32 v66, 0
	v_mov_b32_e32 v67, 0
	v_mov_b32_e32 v68, 0
	v_mov_b32_e32 v69, 0
	v_mov_b32_e32 v70, 0
	v_mov_b32_e32 v71, 0
	v_mov_b32_e32 v72, 0
	v_mov_b32_e32 v73, 0
	v_mov_b32_e32 v74, 0
	v_mov_b32_e32 v75, 0
	v_mov_b32_e32 v76, 0
	v_mov_b32_e32 v77, 0
	v_mov_b32_e32 v78, 0
	v_mov_b32_e32 v79, 0
	v_mov_b32_e32 v80, 0
	v_mov_b32_e32 v81, 0
	v_mov_b32_e32 v82, 0
	v_mov_b32_e32 v83, 0
	s_waitcnt vmcnt(31)
	v_dot4c_i32_i8_e32 v52, v84, v16
	s_waitcnt vmcnt(30)
	v_dot4c_i32_i8_e32 v53, v88, v16
	s_waitcnt vmcnt(29)
	v_dot4c_i32_i8_e32 v54, v92, v16
	s_waitcnt vmcnt(28)
	v_dot4c_i32_i8_e32 v55, v96, v16
	s_waitcnt vmcnt(27)
	v_dot4c_i32_i8_e32 v56, v100, v16
	s_waitcnt vmcnt(26)
	v_dot4c_i32_i8_e32 v57, v104, v16
	s_waitcnt vmcnt(25)
	v_dot4c_i32_i8_e32 v58, v108, v16
	s_waitcnt vmcnt(24)
	v_dot4c_i32_i8_e32 v59, v112, v16
	s_waitcnt vmcnt(23)
	v_dot4c_i32_i8_e32 v60, v116, v16
	s_waitcnt vmcnt(22)
	v_dot4c_i32_i8_e32 v61, v120, v16
	s_waitcnt vmcnt(21)
	v_dot4c_i32_i8_e32 v62, v124, v16
	s_waitcnt vmcnt(20)
	v_dot4c_i32_i8_e32 v63, v128, v16
	s_waitcnt vmcnt(19)
	v_dot4c_i32_i8_e32 v64, v132, v16
	s_waitcnt vmcnt(18)
	v_dot4c_i32_i8_e32 v65, v136, v16
	s_waitcnt vmcnt(17)
	v_dot4c_i32_i8_e32 v66, v140, v16
	s_waitcnt vmcnt(16)
	v_dot4c_i32_i8_e32 v67, v144, v16
	v_dot4c_i32_i8_e32 v52, v85, v17
	v_dot4c_i32_i8_e32 v53, v89, v17
	v_dot4c_i32_i8_e32 v54, v93, v17
	v_dot4c_i32_i8_e32 v55, v97, v17
	v_dot4c_i32_i8_e32 v56, v101, v17
	v_dot4c_i32_i8_e32 v57, v105, v17
	v_dot4c_i32_i8_e32 v58, v109, v17
	v_dot4c_i32_i8_e32 v59, v113, v17
	v_dot4c_i32_i8_e32 v60, v117, v17
	v_dot4c_i32_i8_e32 v61, v121, v17
	v_dot4c_i32_i8_e32 v62, v125, v17
	v_dot4c_i32_i8_e32 v63, v129, v17
	v_dot4c_i32_i8_e32 v64, v133, v17
	v_dot4c_i32_i8_e32 v65, v137, v17
	v_dot4c_i32_i8_e32 v66, v141, v17
	v_dot4c_i32_i8_e32 v67, v145, v17
	v_dot4c_i32_i8_e32 v52, v86, v18
	v_dot4c_i32_i8_e32 v53, v90, v18
	v_dot4c_i32_i8_e32 v54, v94, v18
	v_dot4c_i32_i8_e32 v55, v98, v18
	v_dot4c_i32_i8_e32 v56, v102, v18
	v_dot4c_i32_i8_e32 v57, v106, v18
	v_dot4c_i32_i8_e32 v58, v110, v18
	v_dot4c_i32_i8_e32 v59, v114, v18
	v_dot4c_i32_i8_e32 v60, v118, v18
	v_dot4c_i32_i8_e32 v61, v122, v18
	v_dot4c_i32_i8_e32 v62, v126, v18
	v_dot4c_i32_i8_e32 v63, v130, v18
	v_dot4c_i32_i8_e32 v64, v134, v18
	v_dot4c_i32_i8_e32 v65, v138, v18
	v_dot4c_i32_i8_e32 v66, v142, v18
	v_dot4c_i32_i8_e32 v67, v146, v18
	v_dot4c_i32_i8_e32 v52, v87, v19
	v_dot4c_i32_i8_e32 v53, v91, v19
	v_dot4c_i32_i8_e32 v54, v95, v19
	v_dot4c_i32_i8_e32 v55, v99, v19
	v_dot4c_i32_i8_e32 v56, v103, v19
	v_dot4c_i32_i8_e32 v57, v107, v19
	v_dot4c_i32_i8_e32 v58, v111, v19
	v_dot4c_i32_i8_e32 v59, v115, v19
	v_dot4c_i32_i8_e32 v60, v119, v19
	v_dot4c_i32_i8_e32 v61, v123, v19
	v_dot4c_i32_i8_e32 v62, v127, v19
	v_dot4c_i32_i8_e32 v63, v131, v19
	v_dot4c_i32_i8_e32 v64, v135, v19
	v_dot4c_i32_i8_e32 v65, v139, v19
	v_dot4c_i32_i8_e32 v66, v143, v19
	v_dot4c_i32_i8_e32 v67, v147, v19
	ds_write2_b32 v5, v10, v11 offset0:4 offset1:20
	s_waitcnt lgkmcnt(0)
; DI void wave_lds_sync() { asm volatile("s_waitcnt lgkmcnt(0)" ::: "memory"); __builtin_amdgcn_wave_barrier(); }
; DI void phase9(const Params& p, char* smem, int rep) {
;     ...
;       const int tok = __builtin_amdgcn_readfirstlane(c * 16 + w * 4 + t);
;       const int i0 = IDS[(size_t)tok * 128 + lane], i1 = IDS[(size_t)tok * 128 + 64 + lane];
;       const u32x4 hq = *(const u32x4*)(H2Q + (size_t)tok * D_ + s * 256 + l15 * 16);
;       wave_lds_sync();
;       lw[(lane & 3) * 32 + (lane >> 2)] = i0;
;       lw[(lane & 3) * 32 + 16 + (lane >> 2)] = i1;
;       wave_lds_sync();
;       const unsigned char* ub = U8 + s * 256 + l15 * 16;
; #pragma unroll
;       for (int batch = 0; batch < 2; ++batch) {
;         int ida[16];
; #pragma unroll
;         for (int q = 0; q < 4; ++q) { const int4 v = *(const int4*)(lw + g * 32 + batch * 16 + q * 4); ida[q * 4] = v.x; ida[q * 4 + 1] = v.y; ida[q * 4 + 2] = v.z; ida[q * 4 + 3] = v.w; }
;         u32x4 rows[16];
; #pragma unroll
;         for (int k = 0; k < 16; ++k) rows[k] = *(const u32x4*)(ub + (size_t)ida[k] * 2048);
;         int part[16];
; #pragma unroll
;         for (int k = 0; k < 16; ++k) {
;           int acc = 0;
; #pragma unroll
;           for (int d = 0; d < 4; ++d) acc = __builtin_amdgcn_sdot4((int)rows[k][d], (int)hq[d], acc, false);
;           part[k] = acc;
;         }
;         int q8[8], q4[4], q2[2];
; #pragma unroll
;         for (int k = 0; k < 8; ++k) q8[k] = (b3 ? part[8 + k] : part[k]) + __shfl_xor(b3 ? part[k] : part[8 + k], 8);
; #pragma unroll
;         for (int k = 0; k < 4; ++k) q4[k] = (b2 ? q8[4 + k] : q8[k]) + __shfl_xor(b2 ? q8[k] : q8[4 + k], 4);
; #pragma unroll
;         for (int k = 0; k < 2; ++k) q2[k] = (b1 ? q4[2 + k] : q4[k]) + __shfl_xor(b1 ? q4[k] : q4[2 + k], 2);
;         const int rr = (b0 ? q2[1] : q2[0]) + __shfl_xor(b0 ? q2[0] : q2[1], 1);
;         PA[((size_t)s * T_ + tok) * 128 + 4 * (batch * 16 + l15) + g] = rr;
	ds_read_b128 v[20:23], v6 offset:16
	ds_read_b128 v[24:27], v6 offset:32
	ds_read_b128 v[28:31], v6 offset:48
	ds_read_b128 v[32:35], v6 offset:64
	ds_read_b128 v[36:39], v6 offset:80
	ds_read_b128 v[40:43], v6 offset:96
	ds_read_b128 v[44:47], v6 offset:112
	ds_read_b128 v[48:51], v6 offset:128
	v_add_u32_dpp v84, v52, v52 row_ror:8 row_mask:0xf bank_mask:0x3
	v_add_u32_dpp v84, v60, v60 row_ror:8 row_mask:0xf bank_mask:0xc
	v_add_u32_dpp v85, v53, v53 row_ror:8 row_mask:0xf bank_mask:0x3
	v_add_u32_dpp v85, v61, v61 row_ror:8 row_mask:0xf bank_mask:0xc
	v_add_u32_dpp v86, v54, v54 row_ror:8 row_mask:0xf bank_mask:0x3
	v_add_u32_dpp v86, v62, v62 row_ror:8 row_mask:0xf bank_mask:0xc
	v_add_u32_dpp v87, v55, v55 row_ror:8 row_mask:0xf bank_mask:0x3
	v_add_u32_dpp v87, v63, v63 row_ror:8 row_mask:0xf bank_mask:0xc
	v_add_u32_dpp v88, v56, v56 row_ror:8 row_mask:0xf bank_mask:0x3
	v_add_u32_dpp v88, v64, v64 row_ror:8 row_mask:0xf bank_mask:0xc
	v_add_u32_dpp v89, v57, v57 row_ror:8 row_mask:0xf bank_mask:0x3
	v_add_u32_dpp v89, v65, v65 row_ror:8 row_mask:0xf bank_mask:0xc
	v_add_u32_dpp v90, v58, v58 row_ror:8 row_mask:0xf bank_mask:0x3
	v_add_u32_dpp v90, v66, v66 row_ror:8 row_mask:0xf bank_mask:0xc
	v_add_u32_dpp v91, v59, v59 row_ror:8 row_mask:0xf bank_mask:0x3
	v_add_u32_dpp v91, v67, v67 row_ror:8 row_mask:0xf bank_mask:0xc
	v_add_u32_dpp v92, v84, v84 row_half_mirror row_mask:0xf bank_mask:0x5
	v_add_u32_dpp v92, v88, v88 row_half_mirror row_mask:0xf bank_mask:0xa
	v_add_u32_dpp v93, v85, v85 row_half_mirror row_mask:0xf bank_mask:0x5
	v_add_u32_dpp v93, v89, v89 row_half_mirror row_mask:0xf bank_mask:0xa
	v_add_u32_dpp v94, v86, v86 row_half_mirror row_mask:0xf bank_mask:0x5
	v_add_u32_dpp v94, v90, v90 row_half_mirror row_mask:0xf bank_mask:0xa
	v_add_u32_dpp v95, v87, v87 row_half_mirror row_mask:0xf bank_mask:0x5
	v_add_u32_dpp v95, v91, v91 row_half_mirror row_mask:0xf bank_mask:0xa
	v_add_u32_dpp v96, v92, v92 quad_perm:[2,3,0,1] row_mask:0xf bank_mask:0xf
	v_add_u32_dpp v97, v93, v93 quad_perm:[2,3,0,1] row_mask:0xf bank_mask:0xf
	v_add_u32_dpp v98, v94, v94 quad_perm:[2,3,0,1] row_mask:0xf bank_mask:0xf
	s_nop 0
	v_add_u32_dpp v99, v95, v95 quad_perm:[2,3,0,1] row_mask:0xf bank_mask:0xf
	v_cndmask_b32_e64 v100, v98, v96, s[2:3]
	v_cndmask_b32_e64 v101, v99, v97, s[2:3]
	v_add_u32_e32 v214, s46, v4
	s_nop 1
	v_add_u32_dpp v102, v100, v100 quad_perm:[1,0,3,2] row_mask:0xf bank_mask:0xf
	v_add_u32_dpp v103, v101, v101 quad_perm:[1,0,3,2] row_mask:0xf bank_mask:0xf
	v_cndmask_b32_e64 v104, v103, v102, s[4:5]
	global_store_dword v214, v104, s[14:15]
	s_waitcnt vmcnt(16)
	v_dot4c_i32_i8_e32 v68, v148, v16
	s_waitcnt vmcnt(15)
	v_dot4c_i32_i8_e32 v69, v152, v16
	s_waitcnt vmcnt(14)
	v_dot4c_i32_i8_e32 v70, v156, v16
	s_waitcnt vmcnt(13)
	v_dot4c_i32_i8_e32 v71, v160, v16
	s_waitcnt vmcnt(12)
	v_dot4c_i32_i8_e32 v72, v164, v16
	s_waitcnt vmcnt(11)
	v_dot4c_i32_i8_e32 v73, v168, v16
	s_waitcnt vmcnt(10)
	v_dot4c_i32_i8_e32 v74, v172, v16
	s_waitcnt vmcnt(9)
	v_dot4c_i32_i8_e32 v75, v176, v16
	s_waitcnt vmcnt(8)
	v_dot4c_i32_i8_e32 v76, v180, v16
	s_waitcnt vmcnt(7)
	v_dot4c_i32_i8_e32 v77, v184, v16
	s_waitcnt vmcnt(6)
	v_dot4c_i32_i8_e32 v78, v190, v16
	s_waitcnt vmcnt(5)
	v_dot4c_i32_i8_e32 v79, v194, v16
	s_waitcnt vmcnt(4)
	v_dot4c_i32_i8_e32 v80, v198, v16
	s_waitcnt vmcnt(3)
	v_dot4c_i32_i8_e32 v81, v202, v16
	s_waitcnt vmcnt(2)
	v_dot4c_i32_i8_e32 v82, v206, v16
	s_waitcnt vmcnt(1)
; DI unsigned xb_xcc_id() { return (unsigned)__builtin_amdgcn_s_getreg((3 << 11) | 20) & 0xFu; }
; template <class F>
; DI void xcd_queue(unsigned* ctrs, int nchunks, char* smem, F&& f) {
;   const int x0 = (int)(xb_xcc_id() & 7u);
; #pragma unroll 1
;   for (int k = 0; k < 8; ++k) {
;     const int s = (x0 + k) & 7;
;     for (;;) { const int c = grab(ctrs + 64 * s, smem); if (c >= nchunks) break; f(s, c); }
;   }
; DI void phase9(const Params& p, char* smem, int rep) {
;     ...
;         for (int k = 0; k < 16; ++k) {
;           int acc = 0;
; #pragma unroll
;           for (int d = 0; d < 4; ++d) acc = __builtin_amdgcn_sdot4((int)rows[k][d], (int)hq[d], acc, false);
;           part[k] = acc;
;         }
;         int q8[8], q4[4], q2[2];
; #pragma unroll
;         for (int k = 0; k < 8; ++k) q8[k] = (b3 ? part[8 + k] : part[k]) + __shfl_xor(b3 ? part[k] : part[8 + k], 8);
; #pragma unroll
;         for (int k = 0; k < 4; ++k) q4[k] = (b2 ? q8[4 + k] : q8[k]) + __shfl_xor(b2 ? q8[k] : q8[4 + k], 4);
; #pragma unroll
;         for (int k = 0; k < 2; ++k) q2[k] = (b1 ? q4[2 + k] : q4[k]) + __shfl_xor(b1 ? q4[k] : q4[2 + k], 2);
;         const int rr = (b0 ? q2[1] : q2[0]) + __shfl_xor(b0 ? q2[0] : q2[1], 1);
;         PA[((size_t)s * T_ + tok) * 128 + 4 * (batch * 16 + l15) + g] = rr;
	v_dot4c_i32_i8_e32 v83, v210, v16
	v_dot4c_i32_i8_e32 v68, v149, v17
	v_dot4c_i32_i8_e32 v69, v153, v17
	v_dot4c_i32_i8_e32 v70, v157, v17
	v_dot4c_i32_i8_e32 v71, v161, v17
	v_dot4c_i32_i8_e32 v72, v165, v17
	v_dot4c_i32_i8_e32 v73, v169, v17
	v_dot4c_i32_i8_e32 v74, v173, v17
	v_dot4c_i32_i8_e32 v75, v177, v17
	v_dot4c_i32_i8_e32 v76, v181, v17
	v_dot4c_i32_i8_e32 v77, v185, v17
	v_dot4c_i32_i8_e32 v78, v191, v17
	v_dot4c_i32_i8_e32 v79, v195, v17
	v_dot4c_i32_i8_e32 v80, v199, v17
	v_dot4c_i32_i8_e32 v81, v203, v17
	v_dot4c_i32_i8_e32 v82, v207, v17
	v_dot4c_i32_i8_e32 v83, v211, v17
	v_dot4c_i32_i8_e32 v68, v150, v18
	v_dot4c_i32_i8_e32 v69, v154, v18
	v_dot4c_i32_i8_e32 v70, v158, v18
	v_dot4c_i32_i8_e32 v71, v162, v18
	v_dot4c_i32_i8_e32 v72, v166, v18
	v_dot4c_i32_i8_e32 v73, v170, v18
	v_dot4c_i32_i8_e32 v74, v174, v18
	v_dot4c_i32_i8_e32 v75, v178, v18
	v_dot4c_i32_i8_e32 v76, v182, v18
	v_dot4c_i32_i8_e32 v77, v186, v18
	v_dot4c_i32_i8_e32 v78, v192, v18
	v_dot4c_i32_i8_e32 v79, v196, v18
	v_dot4c_i32_i8_e32 v80, v200, v18
	v_dot4c_i32_i8_e32 v81, v204, v18
	v_dot4c_i32_i8_e32 v82, v208, v18
	v_dot4c_i32_i8_e32 v83, v212, v18
	v_dot4c_i32_i8_e32 v68, v151, v19
	v_dot4c_i32_i8_e32 v69, v155, v19
	v_dot4c_i32_i8_e32 v70, v159, v19
	v_dot4c_i32_i8_e32 v71, v163, v19
	v_dot4c_i32_i8_e32 v72, v167, v19
	v_dot4c_i32_i8_e32 v73, v171, v19
	v_dot4c_i32_i8_e32 v74, v175, v19
	v_dot4c_i32_i8_e32 v75, v179, v19
	v_dot4c_i32_i8_e32 v76, v183, v19
	v_dot4c_i32_i8_e32 v77, v187, v19
	v_dot4c_i32_i8_e32 v78, v193, v19
	v_dot4c_i32_i8_e32 v79, v197, v19
	v_dot4c_i32_i8_e32 v80, v201, v19
	v_dot4c_i32_i8_e32 v81, v205, v19
	v_dot4c_i32_i8_e32 v82, v209, v19
	v_dot4c_i32_i8_e32 v83, v213, v19
	v_add_u32_dpp v148, v68, v68 row_ror:8 row_mask:0xf bank_mask:0x3
	v_add_u32_dpp v148, v76, v76 row_ror:8 row_mask:0xf bank_mask:0xc
	v_add_u32_dpp v149, v69, v69 row_ror:8 row_mask:0xf bank_mask:0x3
	v_add_u32_dpp v149, v77, v77 row_ror:8 row_mask:0xf bank_mask:0xc
	v_add_u32_dpp v150, v70, v70 row_ror:8 row_mask:0xf bank_mask:0x3
	v_add_u32_dpp v150, v78, v78 row_ror:8 row_mask:0xf bank_mask:0xc
	v_add_u32_dpp v151, v71, v71 row_ror:8 row_mask:0xf bank_mask:0x3
	v_add_u32_dpp v151, v79, v79 row_ror:8 row_mask:0xf bank_mask:0xc
	v_add_u32_dpp v152, v72, v72 row_ror:8 row_mask:0xf bank_mask:0x3
	v_add_u32_dpp v152, v80, v80 row_ror:8 row_mask:0xf bank_mask:0xc
	v_add_u32_dpp v153, v73, v73 row_ror:8 row_mask:0xf bank_mask:0x3
	v_add_u32_dpp v153, v81, v81 row_ror:8 row_mask:0xf bank_mask:0xc
	v_add_u32_dpp v154, v74, v74 row_ror:8 row_mask:0xf bank_mask:0x3
	v_add_u32_dpp v154, v82, v82 row_ror:8 row_mask:0xf bank_mask:0xc
	v_add_u32_dpp v155, v75, v75 row_ror:8 row_mask:0xf bank_mask:0x3
	v_add_u32_dpp v155, v83, v83 row_ror:8 row_mask:0xf bank_mask:0xc
	v_add_u32_dpp v156, v148, v148 row_half_mirror row_mask:0xf bank_mask:0x5
	v_add_u32_dpp v156, v152, v152 row_half_mirror row_mask:0xf bank_mask:0xa
	v_add_u32_dpp v157, v149, v149 row_half_mirror row_mask:0xf bank_mask:0x5
	v_add_u32_dpp v157, v153, v153 row_half_mirror row_mask:0xf bank_mask:0xa
	v_add_u32_dpp v158, v150, v150 row_half_mirror row_mask:0xf bank_mask:0x5
	v_add_u32_dpp v158, v154, v154 row_half_mirror row_mask:0xf bank_mask:0xa
	v_add_u32_dpp v159, v151, v151 row_half_mirror row_mask:0xf bank_mask:0x5
	v_add_u32_dpp v159, v155, v155 row_half_mirror row_mask:0xf bank_mask:0xa
	v_add_u32_dpp v160, v156, v156 quad_perm:[2,3,0,1] row_mask:0xf bank_mask:0xf
	v_add_u32_dpp v161, v157, v157 quad_perm:[2,3,0,1] row_mask:0xf bank_mask:0xf
	v_add_u32_dpp v162, v158, v158 quad_perm:[2,3,0,1] row_mask:0xf bank_mask:0xf
	s_nop 0
	v_add_u32_dpp v163, v159, v159 quad_perm:[2,3,0,1] row_mask:0xf bank_mask:0xf
	v_cndmask_b32_e64 v164, v162, v160, s[2:3]
	v_cndmask_b32_e64 v165, v163, v161, s[2:3]
	s_nop 0
	s_nop 1
	v_add_u32_dpp v166, v164, v164 quad_perm:[1,0,3,2] row_mask:0xf bank_mask:0xf
	v_add_u32_dpp v167, v165, v165 quad_perm:[1,0,3,2] row_mask:0xf bank_mask:0xf
	v_cndmask_b32_e64 v168, v167, v166, s[4:5]
	global_store_dword v214, v168, s[14:15] offset:256
	s_add_i32 s48, s48, 1
	s_add_i32 s34, s34, 4
	s_cmp_lt_u32 s48, s49
	s_cbranch_scc0 .Lp9_chunk_done
	s_cmp_lt_u32 s34, 8192
	s_cbranch_scc1 .Lp9_body
	s_branch .Lp9_slice_next
.Lp9_chunk_done:
	s_cmp_eq_u32 s52, 0
	s_cbranch_scc0 .Lp9_grab
.Lp9_peek:
	global_load_dword v215, v216, s[16:17] sc1
	s_waitcnt vmcnt(0)
	s_mov_b32 s52, 1
	s_mov_b32 s18, 0
	s_branch .Lp9_slice
.Lp9_slice_next:
	s_add_i32 s18, s18, 1
	s_cmp_lt_u32 s18, 8
	s_cbranch_scc1 .Lp9_slice
	s_branch .LBB0_1129
